# epilogue sum-of-squares cross-lane adds via v_permlane16/32_swap instead of ds_bpermute round trips (P1 qkv, P5, P7)
# speedup vs baseline: 1.0019x; 1.0019x over previous
; #define GAS __attribute__((address_space(1)))
; __device__ __forceinline__ unsigned cvt_pk_bf16(float lo, float hi) { f32x2 v = {lo, hi}; bf16x2_t b = __builtin_convertvector(v, bf16x2_t); return __builtin_bit_cast(unsigned, b); }
;     __device__ __forceinline__ void operator()(const f32x4 (&acc)[2][2][4][2], const Unit& u, int wr, int wc, int fr, int fq) const {
;     ...
;             for (int m = 0; m < 4; ++m) { const int row = row0 + ai * HALF + m * 16; const float rs = rs1[row]; GAS bf16_t* rowp = base + (size_t)row * 512 + col0;
; #pragma unroll
;                 for (int bj = 0; bj < 2; ++bj) { const f32x4 v0 = acc[ai][bj][m][0] * rs, v1 = acc[ai][bj][m][1] * rs;
;                     u32x4 w; w.x = cvt_pk_bf16(v0[0], v0[1]); w.y = cvt_pk_bf16(v0[2], v0[3]); w.z = cvt_pk_bf16(v1[0], v1[1]); w.w = cvt_pk_bf16(v1[2], v1[3]);
;                     *(GAS u32x4*)(rowp + bj * HALF) = w;
;                     if (sidx >= 0) { float q = ((v0[0] * v0[0] + v0[1] * v0[1]) + (v0[2] * v0[2] + v0[3] * v0[3])) + ((v1[0] * v1[0] + v1[1] * v1[1]) + (v1[2] * v1[2] + v1[3] * v1[3]));
;                         q += __shfl_xor(q, 16); q += __shfl_xor(q, 32);
;                         if (fq == 0) ss[((size_t)sidx * MROWS + row) * 16 + (colt >> 5) + 4 * bj + wc] = q; } } }
.LBB0_186:
	v_ashrrev_i32_e32 v163, 31, v162
	v_lshl_add_u64 v[130:131], v[162:163], 2, s[2:3]
	global_load_dword v206, v[130:131], off
	global_load_dword v207, v[130:131], off offset:64
	global_load_dword v208, v[130:131], off offset:128
	global_load_dword v209, v[130:131], off offset:192
	global_load_dword v210, v[130:131], off offset:512
	global_load_dword v211, v[130:131], off offset:576
	global_load_dword v212, v[130:131], off offset:640
	global_load_dword v213, v[130:131], off offset:704
	s_lshl_b32 s10, s10, 8
	s_ashr_i32 s21, s20, 31
	s_and_b32 s13, s10, 0x100
	s_lshl_b64 s[10:11], s[20:21], 25
	s_add_u32 s10, s42, s10
	v_or_b32_e32 v0, s13, v203
	s_addc_u32 s11, s43, s11
	v_lshlrev_b32_e32 v0, 1, v0
	s_cmp_gt_i32 s72, -1
	v_lshlrev_b64 v[138:139], 10, v[162:163]
	v_lshl_add_u64 v[132:133], s[10:11], 0, v[0:1]
	s_cselect_b64 s[22:23], -1, 0
	s_lshr_b32 s13, s13, 5
	s_lshl_b64 s[20:21], s[72:73], 21
	v_lshlrev_b64 v[134:135], 6, v[162:163]
	v_lshl_add_u64 v[138:139], v[132:133], 0, v[138:139]
	s_cmp_lt_i32 s72, 0
	s_waitcnt vmcnt(0)
	s_nop 1
	v_mov_b32_e32 v136, v206
	v_pk_mul_f32 v[128:129], v[128:129], v[136:137] op_sel_hi:[1,0]
	v_pk_mul_f32 v[126:127], v[126:127], v[136:137] op_sel_hi:[1,0]
	v_pk_mul_f32 v[124:125], v[124:125], v[136:137] op_sel_hi:[1,0]
	v_pk_mul_f32 v[122:123], v[122:123], v[136:137] op_sel_hi:[1,0]
	v_cvt_pk_bf16_f32 v140, v126, v127
	v_cvt_pk_bf16_f32 v141, v128, v129
	v_cvt_pk_bf16_f32 v142, v122, v123
	v_cvt_pk_bf16_f32 v143, v124, v125
	global_store_dwordx4 v[138:139], v[140:143], off
	s_cbranch_scc1 .LBB0_190
	v_mul_f32_e32 v0, v127, v127
	v_mul_f32_e32 v123, v123, v123
	v_fmac_f32_e32 v0, v126, v126
	v_mul_f32_e32 v126, v129, v129
	v_fmac_f32_e32 v123, v122, v122
	v_mul_f32_e32 v122, v125, v125
	v_fmac_f32_e32 v126, v128, v128
	v_fmac_f32_e32 v122, v124, v124
	v_add_f32_e32 v0, v0, v126
	v_add_f32_e32 v122, v123, v122
	v_and_b32_e32 v123, 64, v240
	v_add_f32_e32 v0, v0, v122
	v_add_u32_e32 v123, 64, v123
	v_mov_b32_e32 v122, v0
	s_nop 1
	v_permlane16_swap_b32_e32 v0, v122
	s_waitcnt lgkmcnt(0)
	v_add_f32_e32 v0, v0, v122
	v_mov_b32_e32 v122, v0
	s_nop 1
	v_permlane32_swap_b32_e32 v0, v122
	s_and_saveexec_b64 s[10:11], s[6:7]
	s_cbranch_execz .LBB0_189
	s_add_u32 s24, s44, s20
	s_addc_u32 s25, s45, s21
	v_lshl_add_u64 v[124:125], s[24:25], 0, v[134:135]
	s_lshl_b32 s72, s13, 2
	v_lshl_add_u64 v[124:125], v[124:125], 0, s[72:73]
	s_lshl_b32 s72, s50, 2
	v_lshl_add_u64 v[124:125], v[124:125], 0, s[72:73]
	s_waitcnt lgkmcnt(0)
	v_add_f32_e32 v0, v0, v122
	global_store_dword v[124:125], v0, off

; #define GAS __attribute__((address_space(1)))
; __device__ __forceinline__ unsigned cvt_pk_bf16(float lo, float hi) { f32x2 v = {lo, hi}; bf16x2_t b = __builtin_convertvector(v, bf16x2_t); return __builtin_bit_cast(unsigned, b); }
;     __device__ __forceinline__ void operator()(const f32x4 (&acc)[2][2][4][2], const Unit& u, int wr, int wc, int fr, int fq) const {
;     ...
;             for (int m = 0; m < 4; ++m) { const int row = row0 + ai * HALF + m * 16; const float rs = rs1[row]; GAS bf16_t* rowp = base + (size_t)row * 512 + col0;
; #pragma unroll
;                 for (int bj = 0; bj < 2; ++bj) { const f32x4 v0 = acc[ai][bj][m][0] * rs, v1 = acc[ai][bj][m][1] * rs;
;                     u32x4 w; w.x = cvt_pk_bf16(v0[0], v0[1]); w.y = cvt_pk_bf16(v0[2], v0[3]); w.z = cvt_pk_bf16(v1[0], v1[1]); w.w = cvt_pk_bf16(v1[2], v1[3]);
;                     *(GAS u32x4*)(rowp + bj * HALF) = w;
;                     if (sidx >= 0) { float q = ((v0[0] * v0[0] + v0[1] * v0[1]) + (v0[2] * v0[2] + v0[3] * v0[3])) + ((v1[0] * v1[0] + v1[1] * v1[1]) + (v1[2] * v1[2] + v1[3] * v1[3]));
;                         q += __shfl_xor(q, 16); q += __shfl_xor(q, 32);
;                         if (fq == 0) ss[((size_t)sidx * MROWS + row) * 16 + (colt >> 5) + 4 * bj + wc] = q; } } }
.LBB0_190:
	v_mov_b32_e32 v137, v136
	s_waitcnt lgkmcnt(0)
	v_mov_b32_e32 v122, v136
	v_mov_b32_e32 v123, v136
	v_pk_mul_f32 v[120:121], v[120:121], v[122:123]
	v_pk_mul_f32 v[118:119], v[118:119], v[136:137]
	v_pk_mul_f32 v[116:117], v[116:117], v[122:123]
	v_pk_mul_f32 v[114:115], v[114:115], v[136:137]
	v_cndmask_b32_e64 v0, 0, 1, s[22:23]
	v_cvt_pk_bf16_f32 v122, v118, v119
	v_cvt_pk_bf16_f32 v123, v120, v121
	v_cvt_pk_bf16_f32 v124, v114, v115
	v_cvt_pk_bf16_f32 v125, v116, v117
	v_cmp_ne_u32_e64 s[10:11], 1, v0
	s_andn2_b64 vcc, exec, s[22:23]
	global_store_dwordx4 v[138:139], v[122:125], off offset:256
	s_cbranch_vccnz .LBB0_194
	v_mul_f32_e32 v0, v119, v119
	v_mul_f32_e32 v115, v115, v115
	v_fmac_f32_e32 v0, v118, v118
	v_mul_f32_e32 v118, v121, v121
	v_fmac_f32_e32 v115, v114, v114
	v_mul_f32_e32 v114, v117, v117
	v_fmac_f32_e32 v118, v120, v120
	v_fmac_f32_e32 v114, v116, v116
	v_add_f32_e32 v0, v0, v118
	v_add_f32_e32 v114, v115, v114
	v_and_b32_e32 v115, 64, v240
	v_add_f32_e32 v0, v0, v114
	v_add_u32_e32 v115, 64, v115
	v_mov_b32_e32 v114, v0
	s_nop 1
	v_permlane16_swap_b32_e32 v0, v114
	s_waitcnt lgkmcnt(0)
	v_add_f32_e32 v0, v0, v114
	v_mov_b32_e32 v114, v0
	s_nop 1
	v_permlane32_swap_b32_e32 v0, v114
	s_and_saveexec_b64 s[22:23], s[6:7]
	s_cbranch_execz .LBB0_193
	s_add_u32 s24, s44, s20
	s_addc_u32 s25, s45, s21
	v_lshl_add_u64 v[116:117], s[24:25], 0, v[134:135]
	s_lshl_b32 s72, s13, 2
	v_lshl_add_u64 v[116:117], v[116:117], 0, s[72:73]
	s_lshl_b32 s72, s50, 2
	v_lshl_add_u64 v[116:117], v[116:117], 0, s[72:73]
	s_waitcnt lgkmcnt(0)
	v_add_f32_e32 v0, v0, v114
	global_store_dword v[116:117], v0, off offset:16

; #define GAS __attribute__((address_space(1)))
; __device__ __forceinline__ unsigned cvt_pk_bf16(float lo, float hi) { f32x2 v = {lo, hi}; bf16x2_t b = __builtin_convertvector(v, bf16x2_t); return __builtin_bit_cast(unsigned, b); }
;     __device__ __forceinline__ void operator()(const f32x4 (&acc)[2][2][4][2], const Unit& u, int wr, int wc, int fr, int fq) const {
;     ...
;             for (int m = 0; m < 4; ++m) { const int row = row0 + ai * HALF + m * 16; const float rs = rs1[row]; GAS bf16_t* rowp = base + (size_t)row * 512 + col0;
; #pragma unroll
;                 for (int bj = 0; bj < 2; ++bj) { const f32x4 v0 = acc[ai][bj][m][0] * rs, v1 = acc[ai][bj][m][1] * rs;
;                     u32x4 w; w.x = cvt_pk_bf16(v0[0], v0[1]); w.y = cvt_pk_bf16(v0[2], v0[3]); w.z = cvt_pk_bf16(v1[0], v1[1]); w.w = cvt_pk_bf16(v1[2], v1[3]);
;                     *(GAS u32x4*)(rowp + bj * HALF) = w;
;                     if (sidx >= 0) { float q = ((v0[0] * v0[0] + v0[1] * v0[1]) + (v0[2] * v0[2] + v0[3] * v0[3])) + ((v1[0] * v1[0] + v1[1] * v1[1]) + (v1[2] * v1[2] + v1[3] * v1[3]));
;                         q += __shfl_xor(q, 16); q += __shfl_xor(q, 32);
;                         if (fq == 0) ss[((size_t)sidx * MROWS + row) * 16 + (colt >> 5) + 4 * bj + wc] = q; } } }
.LBB0_194:
	s_waitcnt lgkmcnt(0)
	v_or_b32_e32 v114, 16, v162
	v_ashrrev_i32_e32 v115, 31, v114
	v_lshl_add_u64 v[116:117], v[114:115], 2, s[2:3]
	v_lshlrev_b64 v[116:117], 10, v[114:115]
	v_lshlrev_b64 v[114:115], 6, v[114:115]
	v_lshl_add_u64 v[116:117], v[132:133], 0, v[116:117]
	s_and_b64 vcc, exec, s[10:11]
	s_nop 1
	v_mov_b32_e32 v118, v207
	v_pk_mul_f32 v[112:113], v[112:113], v[118:119] op_sel_hi:[1,0]
	v_pk_mul_f32 v[110:111], v[110:111], v[118:119] op_sel_hi:[1,0]
	v_pk_mul_f32 v[108:109], v[108:109], v[118:119] op_sel_hi:[1,0]
	v_pk_mul_f32 v[106:107], v[106:107], v[118:119] op_sel_hi:[1,0]
	v_cvt_pk_bf16_f32 v120, v110, v111
	v_cvt_pk_bf16_f32 v121, v112, v113
	v_cvt_pk_bf16_f32 v122, v106, v107
	v_cvt_pk_bf16_f32 v123, v108, v109
	global_store_dwordx4 v[116:117], v[120:123], off
	s_cbranch_vccnz .LBB0_198
	v_mul_f32_e32 v0, v111, v111
	v_mul_f32_e32 v107, v107, v107
	v_fmac_f32_e32 v0, v110, v110
	v_mul_f32_e32 v110, v113, v113
	v_fmac_f32_e32 v107, v106, v106
	v_mul_f32_e32 v106, v109, v109
	v_fmac_f32_e32 v110, v112, v112
	v_fmac_f32_e32 v106, v108, v108
	v_add_f32_e32 v0, v0, v110
	v_add_f32_e32 v106, v107, v106
	v_and_b32_e32 v107, 64, v240
	v_add_f32_e32 v0, v0, v106
	v_add_u32_e32 v107, 64, v107
	v_mov_b32_e32 v106, v0
	s_nop 1
	v_permlane16_swap_b32_e32 v0, v106
	s_waitcnt lgkmcnt(0)
	v_add_f32_e32 v0, v0, v106
	v_mov_b32_e32 v106, v0
	s_nop 1
	v_permlane32_swap_b32_e32 v0, v106
	s_and_saveexec_b64 s[22:23], s[6:7]
	s_cbranch_execz .LBB0_197
	s_add_u32 s24, s44, s20
	s_addc_u32 s25, s45, s21
	v_lshl_add_u64 v[108:109], s[24:25], 0, v[114:115]
	s_lshl_b32 s72, s13, 2
	v_lshl_add_u64 v[108:109], v[108:109], 0, s[72:73]
	s_lshl_b32 s72, s50, 2
	v_lshl_add_u64 v[108:109], v[108:109], 0, s[72:73]
	s_waitcnt lgkmcnt(0)
	v_add_f32_e32 v0, v0, v106
	global_store_dword v[108:109], v0, off

; #define GAS __attribute__((address_space(1)))
; __device__ __forceinline__ unsigned cvt_pk_bf16(float lo, float hi) { f32x2 v = {lo, hi}; bf16x2_t b = __builtin_convertvector(v, bf16x2_t); return __builtin_bit_cast(unsigned, b); }
;     __device__ __forceinline__ void operator()(const f32x4 (&acc)[2][2][4][2], const Unit& u, int wr, int wc, int fr, int fq) const {
;     ...
;             for (int m = 0; m < 4; ++m) { const int row = row0 + ai * HALF + m * 16; const float rs = rs1[row]; GAS bf16_t* rowp = base + (size_t)row * 512 + col0;
; #pragma unroll
;                 for (int bj = 0; bj < 2; ++bj) { const f32x4 v0 = acc[ai][bj][m][0] * rs, v1 = acc[ai][bj][m][1] * rs;
;                     u32x4 w; w.x = cvt_pk_bf16(v0[0], v0[1]); w.y = cvt_pk_bf16(v0[2], v0[3]); w.z = cvt_pk_bf16(v1[0], v1[1]); w.w = cvt_pk_bf16(v1[2], v1[3]);
;                     *(GAS u32x4*)(rowp + bj * HALF) = w;
;                     if (sidx >= 0) { float q = ((v0[0] * v0[0] + v0[1] * v0[1]) + (v0[2] * v0[2] + v0[3] * v0[3])) + ((v1[0] * v1[0] + v1[1] * v1[1]) + (v1[2] * v1[2] + v1[3] * v1[3]));
;                         q += __shfl_xor(q, 16); q += __shfl_xor(q, 32);
;                         if (fq == 0) ss[((size_t)sidx * MROWS + row) * 16 + (colt >> 5) + 4 * bj + wc] = q; } } }
.LBB0_198:
	v_mov_b32_e32 v119, v118
	s_waitcnt lgkmcnt(0)
	v_mov_b32_e32 v106, v118
	v_mov_b32_e32 v107, v118
	v_pk_mul_f32 v[104:105], v[104:105], v[106:107]
	v_pk_mul_f32 v[102:103], v[102:103], v[118:119]
	v_pk_mul_f32 v[100:101], v[100:101], v[106:107]
	v_pk_mul_f32 v[98:99], v[98:99], v[118:119]
	v_cvt_pk_bf16_f32 v106, v102, v103
	v_cvt_pk_bf16_f32 v107, v104, v105
	v_cvt_pk_bf16_f32 v108, v98, v99
	v_cvt_pk_bf16_f32 v109, v100, v101
	s_and_b64 vcc, exec, s[10:11]
	global_store_dwordx4 v[116:117], v[106:109], off offset:256
	s_cbranch_vccnz .LBB0_202
	v_mul_f32_e32 v0, v103, v103
	v_mul_f32_e32 v99, v99, v99
	v_fmac_f32_e32 v0, v102, v102
	v_mul_f32_e32 v102, v105, v105
	v_fmac_f32_e32 v99, v98, v98
	v_mul_f32_e32 v98, v101, v101
	v_fmac_f32_e32 v102, v104, v104
	v_fmac_f32_e32 v98, v100, v100
	v_add_f32_e32 v0, v0, v102
	v_add_f32_e32 v98, v99, v98
	v_and_b32_e32 v99, 64, v240
	v_add_f32_e32 v0, v0, v98
	v_add_u32_e32 v99, 64, v99
	v_mov_b32_e32 v98, v0
	s_nop 1
	v_permlane16_swap_b32_e32 v0, v98
	s_waitcnt lgkmcnt(0)
	v_add_f32_e32 v0, v0, v98
	v_mov_b32_e32 v98, v0
	s_nop 1
	v_permlane32_swap_b32_e32 v0, v98
	s_and_saveexec_b64 s[22:23], s[6:7]
	s_cbranch_execz .LBB0_201
	s_add_u32 s24, s44, s20
	s_addc_u32 s25, s45, s21
	v_lshl_add_u64 v[100:101], s[24:25], 0, v[114:115]
	s_lshl_b32 s72, s13, 2
	v_lshl_add_u64 v[100:101], v[100:101], 0, s[72:73]
	s_lshl_b32 s72, s50, 2
	v_lshl_add_u64 v[100:101], v[100:101], 0, s[72:73]
	s_waitcnt lgkmcnt(0)
	v_add_f32_e32 v0, v0, v98
	global_store_dword v[100:101], v0, off offset:16

; #define GAS __attribute__((address_space(1)))
; __device__ __forceinline__ unsigned cvt_pk_bf16(float lo, float hi) { f32x2 v = {lo, hi}; bf16x2_t b = __builtin_convertvector(v, bf16x2_t); return __builtin_bit_cast(unsigned, b); }
;     __device__ __forceinline__ void operator()(const f32x4 (&acc)[2][2][4][2], const Unit& u, int wr, int wc, int fr, int fq) const {
;     ...
;             for (int m = 0; m < 4; ++m) { const int row = row0 + ai * HALF + m * 16; const float rs = rs1[row]; GAS bf16_t* rowp = base + (size_t)row * 512 + col0;
; #pragma unroll
;                 for (int bj = 0; bj < 2; ++bj) { const f32x4 v0 = acc[ai][bj][m][0] * rs, v1 = acc[ai][bj][m][1] * rs;
;                     u32x4 w; w.x = cvt_pk_bf16(v0[0], v0[1]); w.y = cvt_pk_bf16(v0[2], v0[3]); w.z = cvt_pk_bf16(v1[0], v1[1]); w.w = cvt_pk_bf16(v1[2], v1[3]);
;                     *(GAS u32x4*)(rowp + bj * HALF) = w;
;                     if (sidx >= 0) { float q = ((v0[0] * v0[0] + v0[1] * v0[1]) + (v0[2] * v0[2] + v0[3] * v0[3])) + ((v1[0] * v1[0] + v1[1] * v1[1]) + (v1[2] * v1[2] + v1[3] * v1[3]));
;                         q += __shfl_xor(q, 16); q += __shfl_xor(q, 32);
;                         if (fq == 0) ss[((size_t)sidx * MROWS + row) * 16 + (colt >> 5) + 4 * bj + wc] = q; } } }
.LBB0_202:
	s_waitcnt lgkmcnt(0)
	v_or_b32_e32 v98, 32, v162
	v_ashrrev_i32_e32 v99, 31, v98
	v_lshl_add_u64 v[100:101], v[98:99], 2, s[2:3]
	v_lshlrev_b64 v[100:101], 10, v[98:99]
	v_lshlrev_b64 v[98:99], 6, v[98:99]
	v_lshl_add_u64 v[100:101], v[132:133], 0, v[100:101]
	s_and_b64 vcc, exec, s[10:11]
	s_nop 1
	v_mov_b32_e32 v102, v208
	v_pk_mul_f32 v[96:97], v[96:97], v[102:103] op_sel_hi:[1,0]
	v_pk_mul_f32 v[94:95], v[94:95], v[102:103] op_sel_hi:[1,0]
	v_pk_mul_f32 v[92:93], v[92:93], v[102:103] op_sel_hi:[1,0]
	v_pk_mul_f32 v[90:91], v[90:91], v[102:103] op_sel_hi:[1,0]
	v_cvt_pk_bf16_f32 v104, v94, v95
	v_cvt_pk_bf16_f32 v105, v96, v97
	v_cvt_pk_bf16_f32 v106, v90, v91
	v_cvt_pk_bf16_f32 v107, v92, v93
	global_store_dwordx4 v[100:101], v[104:107], off
	s_cbranch_vccnz .LBB0_206
	v_mul_f32_e32 v0, v95, v95
	v_mul_f32_e32 v91, v91, v91
	v_fmac_f32_e32 v0, v94, v94
	v_mul_f32_e32 v94, v97, v97
	v_fmac_f32_e32 v91, v90, v90
	v_mul_f32_e32 v90, v93, v93
	v_fmac_f32_e32 v94, v96, v96
	v_fmac_f32_e32 v90, v92, v92
	v_add_f32_e32 v0, v0, v94
	v_add_f32_e32 v90, v91, v90
	v_and_b32_e32 v91, 64, v240
	v_add_f32_e32 v0, v0, v90
	v_add_u32_e32 v91, 64, v91
	v_mov_b32_e32 v90, v0
	s_nop 1
	v_permlane16_swap_b32_e32 v0, v90
	s_waitcnt lgkmcnt(0)
	v_add_f32_e32 v0, v0, v90
	v_mov_b32_e32 v90, v0
	s_nop 1
	v_permlane32_swap_b32_e32 v0, v90
	s_and_saveexec_b64 s[22:23], s[6:7]
	s_cbranch_execz .LBB0_205
	s_add_u32 s24, s44, s20
	s_addc_u32 s25, s45, s21
	v_lshl_add_u64 v[92:93], s[24:25], 0, v[98:99]
	s_lshl_b32 s72, s13, 2
	v_lshl_add_u64 v[92:93], v[92:93], 0, s[72:73]
	s_lshl_b32 s72, s50, 2
	v_lshl_add_u64 v[92:93], v[92:93], 0, s[72:73]
	s_waitcnt lgkmcnt(0)
	v_add_f32_e32 v0, v0, v90
	global_store_dword v[92:93], v0, off

; #define GAS __attribute__((address_space(1)))
; __device__ __forceinline__ unsigned cvt_pk_bf16(float lo, float hi) { f32x2 v = {lo, hi}; bf16x2_t b = __builtin_convertvector(v, bf16x2_t); return __builtin_bit_cast(unsigned, b); }
;     __device__ __forceinline__ void operator()(const f32x4 (&acc)[2][2][4][2], const Unit& u, int wr, int wc, int fr, int fq) const {
;     ...
;             for (int m = 0; m < 4; ++m) { const int row = row0 + ai * HALF + m * 16; const float rs = rs1[row]; GAS bf16_t* rowp = base + (size_t)row * 512 + col0;
; #pragma unroll
;                 for (int bj = 0; bj < 2; ++bj) { const f32x4 v0 = acc[ai][bj][m][0] * rs, v1 = acc[ai][bj][m][1] * rs;
;                     u32x4 w; w.x = cvt_pk_bf16(v0[0], v0[1]); w.y = cvt_pk_bf16(v0[2], v0[3]); w.z = cvt_pk_bf16(v1[0], v1[1]); w.w = cvt_pk_bf16(v1[2], v1[3]);
;                     *(GAS u32x4*)(rowp + bj * HALF) = w;
;                     if (sidx >= 0) { float q = ((v0[0] * v0[0] + v0[1] * v0[1]) + (v0[2] * v0[2] + v0[3] * v0[3])) + ((v1[0] * v1[0] + v1[1] * v1[1]) + (v1[2] * v1[2] + v1[3] * v1[3]));
;                         q += __shfl_xor(q, 16); q += __shfl_xor(q, 32);
;                         if (fq == 0) ss[((size_t)sidx * MROWS + row) * 16 + (colt >> 5) + 4 * bj + wc] = q; } } }
.LBB0_206:
	v_mov_b32_e32 v103, v102
	s_waitcnt lgkmcnt(0)
	v_mov_b32_e32 v90, v102
	v_mov_b32_e32 v91, v102
	v_pk_mul_f32 v[88:89], v[88:89], v[90:91]
	v_pk_mul_f32 v[86:87], v[86:87], v[102:103]
	v_pk_mul_f32 v[84:85], v[84:85], v[90:91]
	v_pk_mul_f32 v[82:83], v[82:83], v[102:103]
	v_cvt_pk_bf16_f32 v90, v86, v87
	v_cvt_pk_bf16_f32 v91, v88, v89
	v_cvt_pk_bf16_f32 v92, v82, v83
	v_cvt_pk_bf16_f32 v93, v84, v85
	s_and_b64 vcc, exec, s[10:11]
	global_store_dwordx4 v[100:101], v[90:93], off offset:256
	s_cbranch_vccnz .LBB0_210
	v_mul_f32_e32 v0, v87, v87
	v_mul_f32_e32 v83, v83, v83
	v_fmac_f32_e32 v0, v86, v86
	v_mul_f32_e32 v86, v89, v89
	v_fmac_f32_e32 v83, v82, v82
	v_mul_f32_e32 v82, v85, v85
	v_fmac_f32_e32 v86, v88, v88
	v_fmac_f32_e32 v82, v84, v84
	v_add_f32_e32 v0, v0, v86
	v_add_f32_e32 v82, v83, v82
	v_and_b32_e32 v83, 64, v240
	v_add_f32_e32 v0, v0, v82
	v_add_u32_e32 v83, 64, v83
	v_mov_b32_e32 v82, v0
	s_nop 1
	v_permlane16_swap_b32_e32 v0, v82
	s_waitcnt lgkmcnt(0)
	v_add_f32_e32 v0, v0, v82
	v_mov_b32_e32 v82, v0
	s_nop 1
	v_permlane32_swap_b32_e32 v0, v82
	s_and_saveexec_b64 s[22:23], s[6:7]
	s_cbranch_execz .LBB0_209
	s_add_u32 s24, s44, s20
	s_addc_u32 s25, s45, s21
	v_lshl_add_u64 v[84:85], s[24:25], 0, v[98:99]
	s_lshl_b32 s72, s13, 2
	v_lshl_add_u64 v[84:85], v[84:85], 0, s[72:73]
	s_lshl_b32 s72, s50, 2
	v_lshl_add_u64 v[84:85], v[84:85], 0, s[72:73]
	s_waitcnt lgkmcnt(0)
	v_add_f32_e32 v0, v0, v82
	global_store_dword v[84:85], v0, off offset:16

; #define GAS __attribute__((address_space(1)))
; __device__ __forceinline__ unsigned cvt_pk_bf16(float lo, float hi) { f32x2 v = {lo, hi}; bf16x2_t b = __builtin_convertvector(v, bf16x2_t); return __builtin_bit_cast(unsigned, b); }
;     __device__ __forceinline__ void operator()(const f32x4 (&acc)[2][2][4][2], const Unit& u, int wr, int wc, int fr, int fq) const {
;     ...
;             for (int m = 0; m < 4; ++m) { const int row = row0 + ai * HALF + m * 16; const float rs = rs1[row]; GAS bf16_t* rowp = base + (size_t)row * 512 + col0;
; #pragma unroll
;                 for (int bj = 0; bj < 2; ++bj) { const f32x4 v0 = acc[ai][bj][m][0] * rs, v1 = acc[ai][bj][m][1] * rs;
;                     u32x4 w; w.x = cvt_pk_bf16(v0[0], v0[1]); w.y = cvt_pk_bf16(v0[2], v0[3]); w.z = cvt_pk_bf16(v1[0], v1[1]); w.w = cvt_pk_bf16(v1[2], v1[3]);
;                     *(GAS u32x4*)(rowp + bj * HALF) = w;
;                     if (sidx >= 0) { float q = ((v0[0] * v0[0] + v0[1] * v0[1]) + (v0[2] * v0[2] + v0[3] * v0[3])) + ((v1[0] * v1[0] + v1[1] * v1[1]) + (v1[2] * v1[2] + v1[3] * v1[3]));
;                         q += __shfl_xor(q, 16); q += __shfl_xor(q, 32);
;                         if (fq == 0) ss[((size_t)sidx * MROWS + row) * 16 + (colt >> 5) + 4 * bj + wc] = q; } } }
.LBB0_210:
	s_waitcnt lgkmcnt(0)
	v_or_b32_e32 v82, 48, v162
	v_ashrrev_i32_e32 v83, 31, v82
	v_lshl_add_u64 v[84:85], v[82:83], 2, s[2:3]
	v_lshlrev_b64 v[84:85], 10, v[82:83]
	v_lshlrev_b64 v[82:83], 6, v[82:83]
	v_lshl_add_u64 v[84:85], v[132:133], 0, v[84:85]
	s_and_b64 vcc, exec, s[10:11]
	s_nop 1
	v_mov_b32_e32 v86, v209
	v_pk_mul_f32 v[80:81], v[80:81], v[86:87] op_sel_hi:[1,0]
	v_pk_mul_f32 v[78:79], v[78:79], v[86:87] op_sel_hi:[1,0]
	v_pk_mul_f32 v[76:77], v[76:77], v[86:87] op_sel_hi:[1,0]
	v_pk_mul_f32 v[74:75], v[74:75], v[86:87] op_sel_hi:[1,0]
	v_cvt_pk_bf16_f32 v88, v78, v79
	v_cvt_pk_bf16_f32 v89, v80, v81
	v_cvt_pk_bf16_f32 v90, v74, v75
	v_cvt_pk_bf16_f32 v91, v76, v77
	global_store_dwordx4 v[84:85], v[88:91], off
	s_cbranch_vccnz .LBB0_214
	v_mul_f32_e32 v0, v79, v79
	v_mul_f32_e32 v75, v75, v75
	v_fmac_f32_e32 v0, v78, v78
	v_mul_f32_e32 v78, v81, v81
	v_fmac_f32_e32 v75, v74, v74
	v_mul_f32_e32 v74, v77, v77
	v_fmac_f32_e32 v78, v80, v80
	v_fmac_f32_e32 v74, v76, v76
	v_add_f32_e32 v0, v0, v78
	v_add_f32_e32 v74, v75, v74
	v_and_b32_e32 v75, 64, v240
	v_add_f32_e32 v0, v0, v74
	v_add_u32_e32 v75, 64, v75
	v_mov_b32_e32 v74, v0
	s_nop 1
	v_permlane16_swap_b32_e32 v0, v74
	s_waitcnt lgkmcnt(0)
	v_add_f32_e32 v0, v0, v74
	v_mov_b32_e32 v74, v0
	s_nop 1
	v_permlane32_swap_b32_e32 v0, v74
	s_and_saveexec_b64 s[22:23], s[6:7]
	s_cbranch_execz .LBB0_213
	s_add_u32 s24, s44, s20
	s_addc_u32 s25, s45, s21
	v_lshl_add_u64 v[76:77], s[24:25], 0, v[82:83]
	s_lshl_b32 s72, s13, 2
	v_lshl_add_u64 v[76:77], v[76:77], 0, s[72:73]
	s_lshl_b32 s72, s50, 2
	v_lshl_add_u64 v[76:77], v[76:77], 0, s[72:73]
	s_waitcnt lgkmcnt(0)
	v_add_f32_e32 v0, v0, v74
	global_store_dword v[76:77], v0, off

; #define GAS __attribute__((address_space(1)))
; __device__ __forceinline__ unsigned cvt_pk_bf16(float lo, float hi) { f32x2 v = {lo, hi}; bf16x2_t b = __builtin_convertvector(v, bf16x2_t); return __builtin_bit_cast(unsigned, b); }
;     __device__ __forceinline__ void operator()(const f32x4 (&acc)[2][2][4][2], const Unit& u, int wr, int wc, int fr, int fq) const {
;     ...
;             for (int m = 0; m < 4; ++m) { const int row = row0 + ai * HALF + m * 16; const float rs = rs1[row]; GAS bf16_t* rowp = base + (size_t)row * 512 + col0;
; #pragma unroll
;                 for (int bj = 0; bj < 2; ++bj) { const f32x4 v0 = acc[ai][bj][m][0] * rs, v1 = acc[ai][bj][m][1] * rs;
;                     u32x4 w; w.x = cvt_pk_bf16(v0[0], v0[1]); w.y = cvt_pk_bf16(v0[2], v0[3]); w.z = cvt_pk_bf16(v1[0], v1[1]); w.w = cvt_pk_bf16(v1[2], v1[3]);
;                     *(GAS u32x4*)(rowp + bj * HALF) = w;
;                     if (sidx >= 0) { float q = ((v0[0] * v0[0] + v0[1] * v0[1]) + (v0[2] * v0[2] + v0[3] * v0[3])) + ((v1[0] * v1[0] + v1[1] * v1[1]) + (v1[2] * v1[2] + v1[3] * v1[3]));
;                         q += __shfl_xor(q, 16); q += __shfl_xor(q, 32);
;                         if (fq == 0) ss[((size_t)sidx * MROWS + row) * 16 + (colt >> 5) + 4 * bj + wc] = q; } } }
.LBB0_214:
	v_mov_b32_e32 v87, v86
	s_waitcnt lgkmcnt(0)
	v_mov_b32_e32 v74, v86
	v_mov_b32_e32 v75, v86
	v_pk_mul_f32 v[72:73], v[72:73], v[74:75]
	v_pk_mul_f32 v[70:71], v[70:71], v[86:87]
	v_pk_mul_f32 v[68:69], v[68:69], v[74:75]
	v_pk_mul_f32 v[66:67], v[66:67], v[86:87]
	v_cvt_pk_bf16_f32 v74, v70, v71
	v_cvt_pk_bf16_f32 v75, v72, v73
	v_cvt_pk_bf16_f32 v76, v66, v67
	v_cvt_pk_bf16_f32 v77, v68, v69
	s_and_b64 vcc, exec, s[10:11]
	global_store_dwordx4 v[84:85], v[74:77], off offset:256
	s_cbranch_vccnz .LBB0_218
	v_mul_f32_e32 v0, v71, v71
	v_mul_f32_e32 v67, v67, v67
	v_fmac_f32_e32 v0, v70, v70
	v_mul_f32_e32 v70, v73, v73
	v_fmac_f32_e32 v67, v66, v66
	v_mul_f32_e32 v66, v69, v69
	v_fmac_f32_e32 v70, v72, v72
	v_fmac_f32_e32 v66, v68, v68
	v_add_f32_e32 v0, v0, v70
	v_add_f32_e32 v66, v67, v66
	v_and_b32_e32 v67, 64, v240
	v_add_f32_e32 v0, v0, v66
	v_add_u32_e32 v67, 64, v67
	v_mov_b32_e32 v66, v0
	s_nop 1
	v_permlane16_swap_b32_e32 v0, v66
	s_waitcnt lgkmcnt(0)
	v_add_f32_e32 v0, v0, v66
	v_mov_b32_e32 v66, v0
	s_nop 1
	v_permlane32_swap_b32_e32 v0, v66
	s_and_saveexec_b64 s[22:23], s[6:7]
	s_cbranch_execz .LBB0_217
	s_add_u32 s24, s44, s20
	s_addc_u32 s25, s45, s21
	v_lshl_add_u64 v[68:69], s[24:25], 0, v[82:83]
	s_lshl_b32 s72, s13, 2
	v_lshl_add_u64 v[68:69], v[68:69], 0, s[72:73]
	s_lshl_b32 s72, s50, 2
	v_lshl_add_u64 v[68:69], v[68:69], 0, s[72:73]
	s_waitcnt lgkmcnt(0)
	v_add_f32_e32 v0, v0, v66
	global_store_dword v[68:69], v0, off offset:16

; #define GAS __attribute__((address_space(1)))
; __device__ __forceinline__ unsigned cvt_pk_bf16(float lo, float hi) { f32x2 v = {lo, hi}; bf16x2_t b = __builtin_convertvector(v, bf16x2_t); return __builtin_bit_cast(unsigned, b); }
;     __device__ __forceinline__ void operator()(const f32x4 (&acc)[2][2][4][2], const Unit& u, int wr, int wc, int fr, int fq) const {
;     ...
;             for (int m = 0; m < 4; ++m) { const int row = row0 + ai * HALF + m * 16; const float rs = rs1[row]; GAS bf16_t* rowp = base + (size_t)row * 512 + col0;
; #pragma unroll
;                 for (int bj = 0; bj < 2; ++bj) { const f32x4 v0 = acc[ai][bj][m][0] * rs, v1 = acc[ai][bj][m][1] * rs;
;                     u32x4 w; w.x = cvt_pk_bf16(v0[0], v0[1]); w.y = cvt_pk_bf16(v0[2], v0[3]); w.z = cvt_pk_bf16(v1[0], v1[1]); w.w = cvt_pk_bf16(v1[2], v1[3]);
;                     *(GAS u32x4*)(rowp + bj * HALF) = w;
;                     if (sidx >= 0) { float q = ((v0[0] * v0[0] + v0[1] * v0[1]) + (v0[2] * v0[2] + v0[3] * v0[3])) + ((v1[0] * v1[0] + v1[1] * v1[1]) + (v1[2] * v1[2] + v1[3] * v1[3]));
;                         q += __shfl_xor(q, 16); q += __shfl_xor(q, 32);
;                         if (fq == 0) ss[((size_t)sidx * MROWS + row) * 16 + (colt >> 5) + 4 * bj + wc] = q; } } }
.LBB0_218:
	s_waitcnt lgkmcnt(0)
	v_add_u32_e32 v66, 0x80, v162
	v_ashrrev_i32_e32 v67, 31, v66
	v_lshlrev_b64 v[68:69], 10, v[66:67]
	v_lshlrev_b64 v[66:67], 6, v[66:67]
	v_lshl_add_u64 v[68:69], v[132:133], 0, v[68:69]
	s_and_b64 vcc, exec, s[10:11]
	s_nop 1
	v_mov_b32_e32 v70, v210
	v_pk_mul_f32 v[64:65], v[64:65], v[70:71] op_sel_hi:[1,0]
	v_pk_mul_f32 v[62:63], v[62:63], v[70:71] op_sel_hi:[1,0]
	v_pk_mul_f32 v[60:61], v[60:61], v[70:71] op_sel_hi:[1,0]
	v_pk_mul_f32 v[58:59], v[58:59], v[70:71] op_sel_hi:[1,0]
	v_cvt_pk_bf16_f32 v72, v62, v63
	v_cvt_pk_bf16_f32 v73, v64, v65
	v_cvt_pk_bf16_f32 v74, v58, v59
	v_cvt_pk_bf16_f32 v75, v60, v61
	global_store_dwordx4 v[68:69], v[72:75], off
	s_cbranch_vccnz .LBB0_222
	v_mul_f32_e32 v0, v63, v63
	v_mul_f32_e32 v59, v59, v59
	v_fmac_f32_e32 v0, v62, v62
	v_mul_f32_e32 v62, v65, v65
	v_fmac_f32_e32 v59, v58, v58
	v_mul_f32_e32 v58, v61, v61
	v_fmac_f32_e32 v62, v64, v64
	v_fmac_f32_e32 v58, v60, v60
	v_add_f32_e32 v0, v0, v62
	v_add_f32_e32 v58, v59, v58
	v_and_b32_e32 v59, 64, v240
	v_add_f32_e32 v0, v0, v58
	v_add_u32_e32 v59, 64, v59
	v_mov_b32_e32 v58, v0
	s_nop 1
	v_permlane16_swap_b32_e32 v0, v58
	s_waitcnt lgkmcnt(0)
	v_add_f32_e32 v0, v0, v58
	v_mov_b32_e32 v58, v0
	s_nop 1
	v_permlane32_swap_b32_e32 v0, v58
	s_and_saveexec_b64 s[22:23], s[6:7]
	s_cbranch_execz .LBB0_221
	s_add_u32 s24, s44, s20
	s_addc_u32 s25, s45, s21
	v_lshl_add_u64 v[60:61], s[24:25], 0, v[66:67]
	s_lshl_b32 s72, s13, 2
	v_lshl_add_u64 v[60:61], v[60:61], 0, s[72:73]
	s_lshl_b32 s72, s50, 2
	v_lshl_add_u64 v[60:61], v[60:61], 0, s[72:73]
	s_waitcnt lgkmcnt(0)
	v_add_f32_e32 v0, v0, v58
	global_store_dword v[60:61], v0, off

; #define GAS __attribute__((address_space(1)))
; __device__ __forceinline__ unsigned cvt_pk_bf16(float lo, float hi) { f32x2 v = {lo, hi}; bf16x2_t b = __builtin_convertvector(v, bf16x2_t); return __builtin_bit_cast(unsigned, b); }
;     __device__ __forceinline__ void operator()(const f32x4 (&acc)[2][2][4][2], const Unit& u, int wr, int wc, int fr, int fq) const {
;     ...
;             for (int m = 0; m < 4; ++m) { const int row = row0 + ai * HALF + m * 16; const float rs = rs1[row]; GAS bf16_t* rowp = base + (size_t)row * 512 + col0;
; #pragma unroll
;                 for (int bj = 0; bj < 2; ++bj) { const f32x4 v0 = acc[ai][bj][m][0] * rs, v1 = acc[ai][bj][m][1] * rs;
;                     u32x4 w; w.x = cvt_pk_bf16(v0[0], v0[1]); w.y = cvt_pk_bf16(v0[2], v0[3]); w.z = cvt_pk_bf16(v1[0], v1[1]); w.w = cvt_pk_bf16(v1[2], v1[3]);
;                     *(GAS u32x4*)(rowp + bj * HALF) = w;
;                     if (sidx >= 0) { float q = ((v0[0] * v0[0] + v0[1] * v0[1]) + (v0[2] * v0[2] + v0[3] * v0[3])) + ((v1[0] * v1[0] + v1[1] * v1[1]) + (v1[2] * v1[2] + v1[3] * v1[3]));
;                         q += __shfl_xor(q, 16); q += __shfl_xor(q, 32);
;                         if (fq == 0) ss[((size_t)sidx * MROWS + row) * 16 + (colt >> 5) + 4 * bj + wc] = q; } } }
.LBB0_222:
	v_mov_b32_e32 v71, v70
	s_waitcnt lgkmcnt(0)
	v_mov_b32_e32 v58, v70
	v_mov_b32_e32 v59, v70
	v_pk_mul_f32 v[56:57], v[56:57], v[58:59]
	v_pk_mul_f32 v[54:55], v[54:55], v[70:71]
	v_pk_mul_f32 v[52:53], v[52:53], v[58:59]
	v_pk_mul_f32 v[50:51], v[50:51], v[70:71]
	v_cvt_pk_bf16_f32 v58, v54, v55
	v_cvt_pk_bf16_f32 v59, v56, v57
	v_cvt_pk_bf16_f32 v60, v50, v51
	v_cvt_pk_bf16_f32 v61, v52, v53
	s_and_b64 vcc, exec, s[10:11]
	global_store_dwordx4 v[68:69], v[58:61], off offset:256
	s_cbranch_vccnz .LBB0_226
	v_mul_f32_e32 v0, v55, v55
	v_mul_f32_e32 v51, v51, v51
	v_fmac_f32_e32 v0, v54, v54
	v_mul_f32_e32 v54, v57, v57
	v_fmac_f32_e32 v51, v50, v50
	v_mul_f32_e32 v50, v53, v53
	v_fmac_f32_e32 v54, v56, v56
	v_fmac_f32_e32 v50, v52, v52
	v_add_f32_e32 v0, v0, v54
	v_add_f32_e32 v50, v51, v50
	v_and_b32_e32 v51, 64, v240
	v_add_f32_e32 v0, v0, v50
	v_add_u32_e32 v51, 64, v51
	v_mov_b32_e32 v50, v0
	s_nop 1
	v_permlane16_swap_b32_e32 v0, v50
	s_waitcnt lgkmcnt(0)
	v_add_f32_e32 v0, v0, v50
	v_mov_b32_e32 v50, v0
	s_nop 1
	v_permlane32_swap_b32_e32 v0, v50
	s_and_saveexec_b64 s[22:23], s[6:7]
	s_cbranch_execz .LBB0_225
	s_add_u32 s24, s44, s20
	s_addc_u32 s25, s45, s21
	v_lshl_add_u64 v[52:53], s[24:25], 0, v[66:67]
	s_lshl_b32 s72, s13, 2
	v_lshl_add_u64 v[52:53], v[52:53], 0, s[72:73]
	s_lshl_b32 s72, s50, 2
	v_lshl_add_u64 v[52:53], v[52:53], 0, s[72:73]
	s_waitcnt lgkmcnt(0)
	v_add_f32_e32 v0, v0, v50
	global_store_dword v[52:53], v0, off offset:16

; #define GAS __attribute__((address_space(1)))
; __device__ __forceinline__ unsigned cvt_pk_bf16(float lo, float hi) { f32x2 v = {lo, hi}; bf16x2_t b = __builtin_convertvector(v, bf16x2_t); return __builtin_bit_cast(unsigned, b); }
;     __device__ __forceinline__ void operator()(const f32x4 (&acc)[2][2][4][2], const Unit& u, int wr, int wc, int fr, int fq) const {
;     ...
;             for (int m = 0; m < 4; ++m) { const int row = row0 + ai * HALF + m * 16; const float rs = rs1[row]; GAS bf16_t* rowp = base + (size_t)row * 512 + col0;
; #pragma unroll
;                 for (int bj = 0; bj < 2; ++bj) { const f32x4 v0 = acc[ai][bj][m][0] * rs, v1 = acc[ai][bj][m][1] * rs;
;                     u32x4 w; w.x = cvt_pk_bf16(v0[0], v0[1]); w.y = cvt_pk_bf16(v0[2], v0[3]); w.z = cvt_pk_bf16(v1[0], v1[1]); w.w = cvt_pk_bf16(v1[2], v1[3]);
;                     *(GAS u32x4*)(rowp + bj * HALF) = w;
;                     if (sidx >= 0) { float q = ((v0[0] * v0[0] + v0[1] * v0[1]) + (v0[2] * v0[2] + v0[3] * v0[3])) + ((v1[0] * v1[0] + v1[1] * v1[1]) + (v1[2] * v1[2] + v1[3] * v1[3]));
;                         q += __shfl_xor(q, 16); q += __shfl_xor(q, 32);
;                         if (fq == 0) ss[((size_t)sidx * MROWS + row) * 16 + (colt >> 5) + 4 * bj + wc] = q; } } }
.LBB0_226:
	s_waitcnt lgkmcnt(0)
	v_add_u32_e32 v50, 0x90, v162
	v_ashrrev_i32_e32 v51, 31, v50
	v_lshlrev_b64 v[52:53], 10, v[50:51]
	v_lshlrev_b64 v[50:51], 6, v[50:51]
	v_lshl_add_u64 v[52:53], v[132:133], 0, v[52:53]
	s_and_b64 vcc, exec, s[10:11]
	s_nop 1
	v_mov_b32_e32 v54, v211
	v_pk_mul_f32 v[48:49], v[48:49], v[54:55] op_sel_hi:[1,0]
	v_pk_mul_f32 v[46:47], v[46:47], v[54:55] op_sel_hi:[1,0]
	v_pk_mul_f32 v[44:45], v[44:45], v[54:55] op_sel_hi:[1,0]
	v_pk_mul_f32 v[42:43], v[42:43], v[54:55] op_sel_hi:[1,0]
	v_cvt_pk_bf16_f32 v56, v46, v47
	v_cvt_pk_bf16_f32 v57, v48, v49
	v_cvt_pk_bf16_f32 v58, v42, v43
	v_cvt_pk_bf16_f32 v59, v44, v45
	global_store_dwordx4 v[52:53], v[56:59], off
	s_cbranch_vccnz .LBB0_230
	v_mul_f32_e32 v0, v47, v47
	v_mul_f32_e32 v43, v43, v43
	v_fmac_f32_e32 v0, v46, v46
	v_mul_f32_e32 v46, v49, v49
	v_fmac_f32_e32 v43, v42, v42
	v_mul_f32_e32 v42, v45, v45
	v_fmac_f32_e32 v46, v48, v48
	v_fmac_f32_e32 v42, v44, v44
	v_add_f32_e32 v0, v0, v46
	v_add_f32_e32 v42, v43, v42
	v_and_b32_e32 v43, 64, v240
	v_add_f32_e32 v0, v0, v42
	v_add_u32_e32 v43, 64, v43
	v_mov_b32_e32 v42, v0
	s_nop 1
	v_permlane16_swap_b32_e32 v0, v42
	s_waitcnt lgkmcnt(0)
	v_add_f32_e32 v0, v0, v42
	v_mov_b32_e32 v42, v0
	s_nop 1
	v_permlane32_swap_b32_e32 v0, v42
	s_and_saveexec_b64 s[22:23], s[6:7]
	s_cbranch_execz .LBB0_229
	s_add_u32 s24, s44, s20
	s_addc_u32 s25, s45, s21
	v_lshl_add_u64 v[44:45], s[24:25], 0, v[50:51]
	s_lshl_b32 s72, s13, 2
	v_lshl_add_u64 v[44:45], v[44:45], 0, s[72:73]
	s_lshl_b32 s72, s50, 2
	v_lshl_add_u64 v[44:45], v[44:45], 0, s[72:73]
	s_waitcnt lgkmcnt(0)
	v_add_f32_e32 v0, v0, v42
	global_store_dword v[44:45], v0, off

; #define GAS __attribute__((address_space(1)))
; __device__ __forceinline__ unsigned cvt_pk_bf16(float lo, float hi) { f32x2 v = {lo, hi}; bf16x2_t b = __builtin_convertvector(v, bf16x2_t); return __builtin_bit_cast(unsigned, b); }
;     __device__ __forceinline__ void operator()(const f32x4 (&acc)[2][2][4][2], const Unit& u, int wr, int wc, int fr, int fq) const {
;     ...
;             for (int m = 0; m < 4; ++m) { const int row = row0 + ai * HALF + m * 16; const float rs = rs1[row]; GAS bf16_t* rowp = base + (size_t)row * 512 + col0;
; #pragma unroll
;                 for (int bj = 0; bj < 2; ++bj) { const f32x4 v0 = acc[ai][bj][m][0] * rs, v1 = acc[ai][bj][m][1] * rs;
;                     u32x4 w; w.x = cvt_pk_bf16(v0[0], v0[1]); w.y = cvt_pk_bf16(v0[2], v0[3]); w.z = cvt_pk_bf16(v1[0], v1[1]); w.w = cvt_pk_bf16(v1[2], v1[3]);
;                     *(GAS u32x4*)(rowp + bj * HALF) = w;
;                     if (sidx >= 0) { float q = ((v0[0] * v0[0] + v0[1] * v0[1]) + (v0[2] * v0[2] + v0[3] * v0[3])) + ((v1[0] * v1[0] + v1[1] * v1[1]) + (v1[2] * v1[2] + v1[3] * v1[3]));
;                         q += __shfl_xor(q, 16); q += __shfl_xor(q, 32);
;                         if (fq == 0) ss[((size_t)sidx * MROWS + row) * 16 + (colt >> 5) + 4 * bj + wc] = q; } } }
.LBB0_230:
	v_mov_b32_e32 v55, v54
	s_waitcnt lgkmcnt(0)
	v_mov_b32_e32 v42, v54
	v_mov_b32_e32 v43, v54
	v_pk_mul_f32 v[40:41], v[40:41], v[42:43]
	v_pk_mul_f32 v[38:39], v[38:39], v[54:55]
	v_pk_mul_f32 v[36:37], v[36:37], v[42:43]
	v_pk_mul_f32 v[34:35], v[34:35], v[54:55]
	v_cvt_pk_bf16_f32 v42, v38, v39
	v_cvt_pk_bf16_f32 v43, v40, v41
	v_cvt_pk_bf16_f32 v44, v34, v35
	v_cvt_pk_bf16_f32 v45, v36, v37
	s_and_b64 vcc, exec, s[10:11]
	global_store_dwordx4 v[52:53], v[42:45], off offset:256
	s_cbranch_vccnz .LBB0_234
	v_mul_f32_e32 v0, v39, v39
	v_mul_f32_e32 v35, v35, v35
	v_fmac_f32_e32 v0, v38, v38
	v_mul_f32_e32 v38, v41, v41
	v_fmac_f32_e32 v35, v34, v34
	v_mul_f32_e32 v34, v37, v37
	v_fmac_f32_e32 v38, v40, v40
	v_fmac_f32_e32 v34, v36, v36
	v_add_f32_e32 v0, v0, v38
	v_add_f32_e32 v34, v35, v34
	v_and_b32_e32 v35, 64, v240
	v_add_f32_e32 v0, v0, v34
	v_add_u32_e32 v35, 64, v35
	v_mov_b32_e32 v34, v0
	s_nop 1
	v_permlane16_swap_b32_e32 v0, v34
	s_waitcnt lgkmcnt(0)
	v_add_f32_e32 v0, v0, v34
	v_mov_b32_e32 v34, v0
	s_nop 1
	v_permlane32_swap_b32_e32 v0, v34
	s_and_saveexec_b64 s[22:23], s[6:7]
	s_cbranch_execz .LBB0_233
	s_add_u32 s24, s44, s20
	s_addc_u32 s25, s45, s21
	v_lshl_add_u64 v[36:37], s[24:25], 0, v[50:51]
	s_lshl_b32 s72, s13, 2
	v_lshl_add_u64 v[36:37], v[36:37], 0, s[72:73]
	s_lshl_b32 s72, s50, 2
	v_lshl_add_u64 v[36:37], v[36:37], 0, s[72:73]
	s_waitcnt lgkmcnt(0)
	v_add_f32_e32 v0, v0, v34
	global_store_dword v[36:37], v0, off offset:16

; #define GAS __attribute__((address_space(1)))
; __device__ __forceinline__ unsigned cvt_pk_bf16(float lo, float hi) { f32x2 v = {lo, hi}; bf16x2_t b = __builtin_convertvector(v, bf16x2_t); return __builtin_bit_cast(unsigned, b); }
;     __device__ __forceinline__ void operator()(const f32x4 (&acc)[2][2][4][2], const Unit& u, int wr, int wc, int fr, int fq) const {
;     ...
;             for (int m = 0; m < 4; ++m) { const int row = row0 + ai * HALF + m * 16; const float rs = rs1[row]; GAS bf16_t* rowp = base + (size_t)row * 512 + col0;
; #pragma unroll
;                 for (int bj = 0; bj < 2; ++bj) { const f32x4 v0 = acc[ai][bj][m][0] * rs, v1 = acc[ai][bj][m][1] * rs;
;                     u32x4 w; w.x = cvt_pk_bf16(v0[0], v0[1]); w.y = cvt_pk_bf16(v0[2], v0[3]); w.z = cvt_pk_bf16(v1[0], v1[1]); w.w = cvt_pk_bf16(v1[2], v1[3]);
;                     *(GAS u32x4*)(rowp + bj * HALF) = w;
;                     if (sidx >= 0) { float q = ((v0[0] * v0[0] + v0[1] * v0[1]) + (v0[2] * v0[2] + v0[3] * v0[3])) + ((v1[0] * v1[0] + v1[1] * v1[1]) + (v1[2] * v1[2] + v1[3] * v1[3]));
;                         q += __shfl_xor(q, 16); q += __shfl_xor(q, 32);
;                         if (fq == 0) ss[((size_t)sidx * MROWS + row) * 16 + (colt >> 5) + 4 * bj + wc] = q; } } }
.LBB0_234:
	s_waitcnt lgkmcnt(0)
	v_add_u32_e32 v34, 0xa0, v162
	v_ashrrev_i32_e32 v35, 31, v34
	v_lshlrev_b64 v[36:37], 10, v[34:35]
	v_lshlrev_b64 v[34:35], 6, v[34:35]
	v_lshl_add_u64 v[36:37], v[132:133], 0, v[36:37]
	s_and_b64 vcc, exec, s[10:11]
	s_nop 1
	v_mov_b32_e32 v38, v212
	v_pk_mul_f32 v[32:33], v[32:33], v[38:39] op_sel_hi:[1,0]
	v_pk_mul_f32 v[30:31], v[30:31], v[38:39] op_sel_hi:[1,0]
	v_pk_mul_f32 v[28:29], v[28:29], v[38:39] op_sel_hi:[1,0]
	v_pk_mul_f32 v[26:27], v[26:27], v[38:39] op_sel_hi:[1,0]
	v_cvt_pk_bf16_f32 v40, v30, v31
	v_cvt_pk_bf16_f32 v41, v32, v33
	v_cvt_pk_bf16_f32 v42, v26, v27
	v_cvt_pk_bf16_f32 v43, v28, v29
	global_store_dwordx4 v[36:37], v[40:43], off
	s_cbranch_vccnz .LBB0_238
	v_mul_f32_e32 v0, v31, v31
	v_mul_f32_e32 v27, v27, v27
	v_fmac_f32_e32 v0, v30, v30
	v_mul_f32_e32 v30, v33, v33
	v_fmac_f32_e32 v27, v26, v26
	v_mul_f32_e32 v26, v29, v29
	v_fmac_f32_e32 v30, v32, v32
	v_fmac_f32_e32 v26, v28, v28
	v_add_f32_e32 v0, v0, v30
	v_add_f32_e32 v26, v27, v26
	v_and_b32_e32 v27, 64, v240
	v_add_f32_e32 v0, v0, v26
	v_add_u32_e32 v27, 64, v27
	v_mov_b32_e32 v26, v0
	s_nop 1
	v_permlane16_swap_b32_e32 v0, v26
	s_waitcnt lgkmcnt(0)
	v_add_f32_e32 v0, v0, v26
	v_mov_b32_e32 v26, v0
	s_nop 1
	v_permlane32_swap_b32_e32 v0, v26
	s_and_saveexec_b64 s[22:23], s[6:7]
	s_cbranch_execz .LBB0_237
	s_add_u32 s24, s44, s20
	s_addc_u32 s25, s45, s21
	v_lshl_add_u64 v[28:29], s[24:25], 0, v[34:35]
	s_lshl_b32 s72, s13, 2
	v_lshl_add_u64 v[28:29], v[28:29], 0, s[72:73]
	s_lshl_b32 s72, s50, 2
	v_lshl_add_u64 v[28:29], v[28:29], 0, s[72:73]
	s_waitcnt lgkmcnt(0)
	v_add_f32_e32 v0, v0, v26
	global_store_dword v[28:29], v0, off

; #define GAS __attribute__((address_space(1)))
; __device__ __forceinline__ unsigned cvt_pk_bf16(float lo, float hi) { f32x2 v = {lo, hi}; bf16x2_t b = __builtin_convertvector(v, bf16x2_t); return __builtin_bit_cast(unsigned, b); }
;     __device__ __forceinline__ void operator()(const f32x4 (&acc)[2][2][4][2], const Unit& u, int wr, int wc, int fr, int fq) const {
;     ...
;             for (int m = 0; m < 4; ++m) { const int row = row0 + ai * HALF + m * 16; const float rs = rs1[row]; GAS bf16_t* rowp = base + (size_t)row * 512 + col0;
; #pragma unroll
;                 for (int bj = 0; bj < 2; ++bj) { const f32x4 v0 = acc[ai][bj][m][0] * rs, v1 = acc[ai][bj][m][1] * rs;
;                     u32x4 w; w.x = cvt_pk_bf16(v0[0], v0[1]); w.y = cvt_pk_bf16(v0[2], v0[3]); w.z = cvt_pk_bf16(v1[0], v1[1]); w.w = cvt_pk_bf16(v1[2], v1[3]);
;                     *(GAS u32x4*)(rowp + bj * HALF) = w;
;                     if (sidx >= 0) { float q = ((v0[0] * v0[0] + v0[1] * v0[1]) + (v0[2] * v0[2] + v0[3] * v0[3])) + ((v1[0] * v1[0] + v1[1] * v1[1]) + (v1[2] * v1[2] + v1[3] * v1[3]));
;                         q += __shfl_xor(q, 16); q += __shfl_xor(q, 32);
;                         if (fq == 0) ss[((size_t)sidx * MROWS + row) * 16 + (colt >> 5) + 4 * bj + wc] = q; } } }
.LBB0_238:
	v_mov_b32_e32 v39, v38
	s_waitcnt lgkmcnt(0)
	v_mov_b32_e32 v26, v38
	v_mov_b32_e32 v27, v38
	v_pk_mul_f32 v[24:25], v[24:25], v[26:27]
	v_pk_mul_f32 v[22:23], v[22:23], v[38:39]
	v_pk_mul_f32 v[20:21], v[20:21], v[26:27]
	v_pk_mul_f32 v[18:19], v[18:19], v[38:39]
	v_cvt_pk_bf16_f32 v26, v22, v23
	v_cvt_pk_bf16_f32 v27, v24, v25
	v_cvt_pk_bf16_f32 v28, v18, v19
	v_cvt_pk_bf16_f32 v29, v20, v21
	s_and_b64 vcc, exec, s[10:11]
	global_store_dwordx4 v[36:37], v[26:29], off offset:256
	s_cbranch_vccnz .LBB0_242
	v_mul_f32_e32 v0, v23, v23
	v_mul_f32_e32 v19, v19, v19
	v_fmac_f32_e32 v0, v22, v22
	v_mul_f32_e32 v22, v25, v25
	v_fmac_f32_e32 v19, v18, v18
	v_mul_f32_e32 v18, v21, v21
	v_fmac_f32_e32 v22, v24, v24
	v_fmac_f32_e32 v18, v20, v20
	v_add_f32_e32 v0, v0, v22
	v_add_f32_e32 v18, v19, v18
	v_and_b32_e32 v19, 64, v240
	v_add_f32_e32 v0, v0, v18
	v_add_u32_e32 v19, 64, v19
	v_mov_b32_e32 v18, v0
	s_nop 1
	v_permlane16_swap_b32_e32 v0, v18
	s_waitcnt lgkmcnt(0)
	v_add_f32_e32 v0, v0, v18
	v_mov_b32_e32 v18, v0
	s_nop 1
	v_permlane32_swap_b32_e32 v0, v18
	s_and_saveexec_b64 s[22:23], s[6:7]
	s_cbranch_execz .LBB0_241
	s_add_u32 s24, s44, s20
	s_addc_u32 s25, s45, s21
	v_lshl_add_u64 v[20:21], s[24:25], 0, v[34:35]
	s_lshl_b32 s72, s13, 2
	v_lshl_add_u64 v[20:21], v[20:21], 0, s[72:73]
	s_lshl_b32 s72, s50, 2
	v_lshl_add_u64 v[20:21], v[20:21], 0, s[72:73]
	s_waitcnt lgkmcnt(0)
	v_add_f32_e32 v0, v0, v18
	global_store_dword v[20:21], v0, off offset:16

; #define GAS __attribute__((address_space(1)))
; __device__ __forceinline__ unsigned cvt_pk_bf16(float lo, float hi) { f32x2 v = {lo, hi}; bf16x2_t b = __builtin_convertvector(v, bf16x2_t); return __builtin_bit_cast(unsigned, b); }
;     __device__ __forceinline__ void operator()(const f32x4 (&acc)[2][2][4][2], const Unit& u, int wr, int wc, int fr, int fq) const {
;     ...
;             for (int m = 0; m < 4; ++m) { const int row = row0 + ai * HALF + m * 16; const float rs = rs1[row]; GAS bf16_t* rowp = base + (size_t)row * 512 + col0;
; #pragma unroll
;                 for (int bj = 0; bj < 2; ++bj) { const f32x4 v0 = acc[ai][bj][m][0] * rs, v1 = acc[ai][bj][m][1] * rs;
;                     u32x4 w; w.x = cvt_pk_bf16(v0[0], v0[1]); w.y = cvt_pk_bf16(v0[2], v0[3]); w.z = cvt_pk_bf16(v1[0], v1[1]); w.w = cvt_pk_bf16(v1[2], v1[3]);
;                     *(GAS u32x4*)(rowp + bj * HALF) = w;
;                     if (sidx >= 0) { float q = ((v0[0] * v0[0] + v0[1] * v0[1]) + (v0[2] * v0[2] + v0[3] * v0[3])) + ((v1[0] * v1[0] + v1[1] * v1[1]) + (v1[2] * v1[2] + v1[3] * v1[3]));
;                         q += __shfl_xor(q, 16); q += __shfl_xor(q, 32);
;                         if (fq == 0) ss[((size_t)sidx * MROWS + row) * 16 + (colt >> 5) + 4 * bj + wc] = q; } } }
.LBB0_242:
	s_waitcnt lgkmcnt(0)
	v_add_u32_e32 v18, 0xb0, v162
	v_ashrrev_i32_e32 v19, 31, v18
	v_lshlrev_b64 v[20:21], 10, v[18:19]
	v_lshlrev_b64 v[18:19], 6, v[18:19]
	v_lshl_add_u64 v[20:21], v[132:133], 0, v[20:21]
	s_and_b64 vcc, exec, s[10:11]
	s_nop 1
	v_mov_b32_e32 v22, v213
	v_pk_mul_f32 v[16:17], v[16:17], v[22:23] op_sel_hi:[1,0]
	v_pk_mul_f32 v[14:15], v[14:15], v[22:23] op_sel_hi:[1,0]
	v_pk_mul_f32 v[12:13], v[12:13], v[22:23] op_sel_hi:[1,0]
	v_pk_mul_f32 v[10:11], v[10:11], v[22:23] op_sel_hi:[1,0]
	v_cvt_pk_bf16_f32 v24, v14, v15
	v_cvt_pk_bf16_f32 v25, v16, v17
	v_cvt_pk_bf16_f32 v26, v10, v11
	v_cvt_pk_bf16_f32 v27, v12, v13
	global_store_dwordx4 v[20:21], v[24:27], off
	s_cbranch_vccnz .LBB0_246
	v_mul_f32_e32 v0, v15, v15
	v_mul_f32_e32 v11, v11, v11
	v_fmac_f32_e32 v0, v14, v14
	v_mul_f32_e32 v14, v17, v17
	v_fmac_f32_e32 v11, v10, v10
	v_mul_f32_e32 v10, v13, v13
	v_fmac_f32_e32 v14, v16, v16
	v_fmac_f32_e32 v10, v12, v12
	v_add_f32_e32 v0, v0, v14
	v_add_f32_e32 v10, v11, v10
	v_and_b32_e32 v11, 64, v240
	v_add_f32_e32 v0, v0, v10
	v_add_u32_e32 v11, 64, v11
	v_mov_b32_e32 v10, v0
	s_nop 1
	v_permlane16_swap_b32_e32 v0, v10
	s_waitcnt lgkmcnt(0)
	v_add_f32_e32 v0, v0, v10
	v_mov_b32_e32 v10, v0
	s_nop 1
	v_permlane32_swap_b32_e32 v0, v10
	s_and_saveexec_b64 s[22:23], s[6:7]
	s_cbranch_execz .LBB0_245
	s_add_u32 s24, s44, s20
	s_addc_u32 s25, s45, s21
	v_lshl_add_u64 v[12:13], s[24:25], 0, v[18:19]
	s_lshl_b32 s72, s13, 2
	v_lshl_add_u64 v[12:13], v[12:13], 0, s[72:73]
	s_lshl_b32 s72, s50, 2
	v_lshl_add_u64 v[12:13], v[12:13], 0, s[72:73]
	s_waitcnt lgkmcnt(0)
	v_add_f32_e32 v0, v0, v10
	global_store_dword v[12:13], v0, off

; #define GAS __attribute__((address_space(1)))
; __device__ __forceinline__ unsigned cvt_pk_bf16(float lo, float hi) { f32x2 v = {lo, hi}; bf16x2_t b = __builtin_convertvector(v, bf16x2_t); return __builtin_bit_cast(unsigned, b); }
;     __device__ __forceinline__ void operator()(const f32x4 (&acc)[2][2][4][2], const Unit& u, int wr, int wc, int fr, int fq) const {
;     ...
;             for (int m = 0; m < 4; ++m) { const int row = row0 + ai * HALF + m * 16; const float rs = rs1[row]; GAS bf16_t* rowp = base + (size_t)row * 512 + col0;
; #pragma unroll
;                 for (int bj = 0; bj < 2; ++bj) { const f32x4 v0 = acc[ai][bj][m][0] * rs, v1 = acc[ai][bj][m][1] * rs;
;                     u32x4 w; w.x = cvt_pk_bf16(v0[0], v0[1]); w.y = cvt_pk_bf16(v0[2], v0[3]); w.z = cvt_pk_bf16(v1[0], v1[1]); w.w = cvt_pk_bf16(v1[2], v1[3]);
;                     *(GAS u32x4*)(rowp + bj * HALF) = w;
;                     if (sidx >= 0) { float q = ((v0[0] * v0[0] + v0[1] * v0[1]) + (v0[2] * v0[2] + v0[3] * v0[3])) + ((v1[0] * v1[0] + v1[1] * v1[1]) + (v1[2] * v1[2] + v1[3] * v1[3]));
;                         q += __shfl_xor(q, 16); q += __shfl_xor(q, 32);
;                         if (fq == 0) ss[((size_t)sidx * MROWS + row) * 16 + (colt >> 5) + 4 * bj + wc] = q; } } }
.LBB0_246:
	v_mov_b32_e32 v23, v22
	s_waitcnt lgkmcnt(0)
	v_mov_b32_e32 v10, v22
	v_mov_b32_e32 v11, v22
	v_pk_mul_f32 v[8:9], v[8:9], v[10:11]
	v_pk_mul_f32 v[6:7], v[6:7], v[22:23]
	v_pk_mul_f32 v[4:5], v[4:5], v[10:11]
	v_pk_mul_f32 v[2:3], v[2:3], v[22:23]
	v_cvt_pk_bf16_f32 v10, v6, v7
	v_cvt_pk_bf16_f32 v11, v8, v9
	v_cvt_pk_bf16_f32 v12, v2, v3
	v_cvt_pk_bf16_f32 v13, v4, v5
	s_and_b64 vcc, exec, s[10:11]
	global_store_dwordx4 v[20:21], v[10:13], off offset:256
	s_cbranch_vccnz .LBB0_250
	v_mul_f32_e32 v0, v7, v7
	v_mul_f32_e32 v3, v3, v3
	v_fmac_f32_e32 v0, v6, v6
	v_mul_f32_e32 v6, v9, v9
	v_fmac_f32_e32 v3, v2, v2
	v_mul_f32_e32 v2, v5, v5
	v_fmac_f32_e32 v6, v8, v8
	v_fmac_f32_e32 v2, v4, v4
	v_add_f32_e32 v0, v0, v6
	v_add_f32_e32 v2, v3, v2
	v_and_b32_e32 v3, 64, v240
	v_add_f32_e32 v0, v0, v2
	v_add_u32_e32 v3, 64, v3
	v_mov_b32_e32 v2, v0
	s_nop 1
	v_permlane16_swap_b32_e32 v0, v2
	s_waitcnt lgkmcnt(0)
	v_add_f32_e32 v0, v0, v2
	v_mov_b32_e32 v2, v0
	s_nop 1
	v_permlane32_swap_b32_e32 v0, v2
	s_and_saveexec_b64 s[10:11], s[6:7]
	s_cbranch_execz .LBB0_249
	s_add_u32 s20, s44, s20
	s_addc_u32 s21, s45, s21
	v_lshl_add_u64 v[4:5], s[20:21], 0, v[18:19]
	s_lshl_b32 s72, s13, 2
	v_lshl_add_u64 v[4:5], v[4:5], 0, s[72:73]
	s_lshl_b32 s72, s50, 2
	v_lshl_add_u64 v[4:5], v[4:5], 0, s[72:73]
	s_waitcnt lgkmcnt(0)
	v_add_f32_e32 v0, v0, v2
	global_store_dword v[4:5], v0, off offset:16

; #define GAS __attribute__((address_space(1)))
; __device__ __forceinline__ unsigned cvt_pk_bf16(float lo, float hi) { f32x2 v = {lo, hi}; bf16x2_t b = __builtin_convertvector(v, bf16x2_t); return __builtin_bit_cast(unsigned, b); }
; __device__ __forceinline__ float bf_lo(unsigned u) { return __uint_as_float(u << 16); }
; __device__ __forceinline__ float bf_hi(unsigned u) { return __uint_as_float(u & 0xffff0000u); }
;     __device__ __forceinline__ void operator()(const f32x4 (&acc)[2][2][4][2], const Unit& u, int wr, int wc, int fr, int fq) const {
;     ...
;             for (int m = 0; m < 4; ++m) { const int row = row0 + ai * HALF + m * 16; const size_t off = (size_t)row * 1024 + col0; float q = 0.f;
; #pragma unroll
;                 for (int bj = 0; bj < 2; ++bj) { const u32x4 xo = *(const GAS u32x4*)(xb + off + bj * HALF);
;                     f32x4 v0 = acc[ai][bj][m][0], v1 = acc[ai][bj][m][1];
;                     v0[0] += bf_lo(xo.x); v0[1] += bf_hi(xo.x); v0[2] += bf_lo(xo.y); v0[3] += bf_hi(xo.y); v1[0] += bf_lo(xo.z); v1[1] += bf_hi(xo.z); v1[2] += bf_lo(xo.w); v1[3] += bf_hi(xo.w);
;                     if (out) { *(GAS f32x4*)(out + off + bj * HALF) = v0; *(GAS f32x4*)(out + off + bj * HALF + 4) = v1; }
;                     u32x4 w; w.x = cvt_pk_bf16(v0[0], v0[1]); w.y = cvt_pk_bf16(v0[2], v0[3]); w.z = cvt_pk_bf16(v1[0], v1[1]); w.w = cvt_pk_bf16(v1[2], v1[3]);
;                     *(GAS u32x4*)(xb + off + bj * HALF) = w;
;                     q += ((v0[0] * v0[0] + v0[1] * v0[1]) + (v0[2] * v0[2] + v0[3] * v0[3])) + ((v1[0] * v1[0] + v1[1] * v1[1]) + (v1[2] * v1[2] + v1[3] * v1[3])); }
;                 q += __shfl_xor(q, 16); q += __shfl_xor(q, 32);
;                 if (fq == 0) rowss[(size_t)row * 16 + u.pn * 4 + wc] = q; }
.LBB0_666:
	v_and_b32_e32 v144, 64, v240
	v_xor_b32_e32 v143, 16, v240
	v_add_u32_e32 v144, 64, v144
	v_cmp_lt_i32_e32 vcc, v143, v144
	v_lshl_add_u32 v142, s22, 8, v146
	v_lshl_or_b32 v140, s20, 8, v148
	v_cndmask_b32_e32 v143, v240, v143, vcc
	v_lshlrev_b32_e32 v151, 2, v143
	v_xor_b32_e32 v143, 32, v240
	v_cmp_lt_i32_e32 vcc, v143, v144
	v_ashrrev_i32_e32 v141, 31, v140
	s_lshl_b32 s20, s20, 2
	v_cndmask_b32_e32 v143, v240, v143, vcc
	v_lshlrev_b32_e32 v150, 2, v143
	v_ashrrev_i32_e32 v143, 31, v142
	v_lshlrev_b64 v[144:145], 11, v[142:143]
	v_lshl_add_u64 v[144:145], s[2:3], 0, v[144:145]
	v_lshl_add_u64 v[144:145], v[140:141], 1, v[144:145]
	s_ashr_i32 s21, s20, 31
	v_lshlrev_b32_e32 v224, 11, v142
	v_lshl_add_u32 v224, v140, 1, v224
	global_load_dwordx4 v[192:195], v224, s[2:3]
	global_load_dwordx4 v[196:199], v224, s[2:3] offset:256
	v_add_u32_e32 v225, 0x8000, v224
	global_load_dwordx4 v[200:203], v225, s[2:3]
	global_load_dwordx4 v[204:207], v225, s[2:3] offset:256
	v_add_u32_e32 v225, 0x10000, v224
	global_load_dwordx4 v[208:211], v225, s[2:3]
	global_load_dwordx4 v[212:215], v225, s[2:3] offset:256
	v_add_u32_e32 v225, 0x18000, v224
	global_load_dwordx4 v[216:219], v225, s[2:3]
	global_load_dwordx4 v[220:223], v225, s[2:3] offset:256
	s_waitcnt vmcnt(0)
	s_nop 1
	v_mov_b32_e32 v152, v192
	v_mov_b32_e32 v153, v193
	v_mov_b32_e32 v154, v194
	v_mov_b32_e32 v155, v195
	v_lshlrev_b32_e32 v156, 16, v152
	v_and_b32_e32 v157, 0xffff0000, v152
	v_lshlrev_b32_e32 v152, 16, v153
	v_and_b32_e32 v153, 0xffff0000, v153
	v_pk_add_f32 v[128:129], v[128:129], v[152:153]
	v_lshlrev_b32_e32 v152, 16, v154
	v_and_b32_e32 v153, 0xffff0000, v154
	v_pk_add_f32 v[152:153], v[122:123], v[152:153]
	v_lshlrev_b32_e32 v122, 16, v155
	v_and_b32_e32 v123, 0xffff0000, v155
	v_pk_add_f32 v[126:127], v[126:127], v[156:157]
	v_pk_add_f32 v[154:155], v[124:125], v[122:123]
	v_cvt_pk_bf16_f32 v122, v126, v127
	v_cvt_pk_bf16_f32 v123, v128, v129
	v_cvt_pk_bf16_f32 v124, v152, v153
	v_cvt_pk_bf16_f32 v125, v154, v155
	global_store_dwordx4 v[144:145], v[122:125], off
	s_nop 1
	v_pk_mul_f32 v[122:123], v[126:127], v[126:127]
	v_pk_mul_f32 v[124:125], v[128:129], v[128:129]
	v_pk_mul_f32 v[126:127], v[152:153], v[152:153]
	v_pk_mul_f32 v[128:129], v[154:155], v[154:155]
	s_nop 1
	v_mov_b32_e32 v152, v196
	v_mov_b32_e32 v153, v197
	v_mov_b32_e32 v154, v198
	v_mov_b32_e32 v155, v199
	v_lshlrev_b32_e32 v156, 16, v152
	v_and_b32_e32 v157, 0xffff0000, v152
	v_lshlrev_b32_e32 v152, 16, v153
	v_and_b32_e32 v153, 0xffff0000, v153
	v_pk_add_f32 v[120:121], v[120:121], v[152:153]
	v_lshlrev_b32_e32 v152, 16, v154
	v_and_b32_e32 v153, 0xffff0000, v154
	v_pk_add_f32 v[152:153], v[114:115], v[152:153]
	v_lshlrev_b32_e32 v114, 16, v155
	v_and_b32_e32 v115, 0xffff0000, v155
	v_pk_add_f32 v[118:119], v[118:119], v[156:157]
	v_pk_add_f32 v[154:155], v[116:117], v[114:115]
	v_cvt_pk_bf16_f32 v114, v118, v119
	v_cvt_pk_bf16_f32 v115, v120, v121
	v_cvt_pk_bf16_f32 v116, v152, v153
	v_cvt_pk_bf16_f32 v117, v154, v155
	global_store_dwordx4 v[144:145], v[114:117], off offset:256
	s_nop 1
	v_pk_mul_f32 v[114:115], v[118:119], v[118:119]
	v_pk_mul_f32 v[116:117], v[120:121], v[120:121]
	v_add_f32_e32 v114, v114, v115
	v_add_f32_e32 v116, v116, v117
	v_pk_mul_f32 v[118:119], v[152:153], v[152:153]
	v_pk_mul_f32 v[120:121], v[154:155], v[154:155]
	v_add_f32_e32 v114, v114, v116
	v_add_f32_e32 v115, v128, v129
	v_add_f32_e32 v116, v126, v127
	v_add_f32_e32 v120, v120, v121
	v_add_f32_e32 v118, v118, v119
	v_add_f32_e32 v115, v116, v115
	v_add_f32_e32 v116, v124, v125
	v_add_f32_e32 v117, v122, v123
	v_add_f32_e32 v118, v118, v120
	v_add_f32_e32 v116, v117, v116
	v_add_f32_e32 v114, v114, v118
	v_add_f32_e32 v115, v116, v115
	v_add_f32_e32 v114, v115, v114
	v_mov_b32_e32 v115, v114
	s_nop 1
	v_permlane16_swap_b32_e32 v114, v115
	s_waitcnt lgkmcnt(0)
	v_add_f32_e32 v114, v114, v115
	v_mov_b32_e32 v115, v114
	s_nop 1
	v_permlane32_swap_b32_e32 v114, v115
	s_and_saveexec_b64 s[22:23], s[6:7]
	s_mov_b32 s28, s58
	s_cbranch_execz .LBB0_668
	v_lshlrev_b64 v[116:117], 6, v[142:143]
	v_lshl_add_u64 v[116:117], s[4:5], 0, v[116:117]
	v_lshl_add_u64 v[116:117], s[20:21], 2, v[116:117]
	s_lshl_b32 s72, s42, 2
	v_lshl_add_u64 v[116:117], v[116:117], 0, s[72:73]
	s_waitcnt lgkmcnt(0)
	v_add_f32_e32 v114, v114, v115
	global_store_dword v[116:117], v114, off
; #define GAS __attribute__((address_space(1)))
; __device__ __forceinline__ unsigned cvt_pk_bf16(float lo, float hi) { f32x2 v = {lo, hi}; bf16x2_t b = __builtin_convertvector(v, bf16x2_t); return __builtin_bit_cast(unsigned, b); }
; __device__ __forceinline__ float bf_lo(unsigned u) { return __uint_as_float(u << 16); }
; __device__ __forceinline__ float bf_hi(unsigned u) { return __uint_as_float(u & 0xffff0000u); }
;     __device__ __forceinline__ void operator()(const f32x4 (&acc)[2][2][4][2], const Unit& u, int wr, int wc, int fr, int fq) const {
;     ...
;             for (int m = 0; m < 4; ++m) { const int row = row0 + ai * HALF + m * 16; const size_t off = (size_t)row * 1024 + col0; float q = 0.f;
; #pragma unroll
;                 for (int bj = 0; bj < 2; ++bj) { const u32x4 xo = *(const GAS u32x4*)(xb + off + bj * HALF);
;                     f32x4 v0 = acc[ai][bj][m][0], v1 = acc[ai][bj][m][1];
;                     v0[0] += bf_lo(xo.x); v0[1] += bf_hi(xo.x); v0[2] += bf_lo(xo.y); v0[3] += bf_hi(xo.y); v1[0] += bf_lo(xo.z); v1[1] += bf_hi(xo.z); v1[2] += bf_lo(xo.w); v1[3] += bf_hi(xo.w);
;                     if (out) { *(GAS f32x4*)(out + off + bj * HALF) = v0; *(GAS f32x4*)(out + off + bj * HALF + 4) = v1; }
;                     u32x4 w; w.x = cvt_pk_bf16(v0[0], v0[1]); w.y = cvt_pk_bf16(v0[2], v0[3]); w.z = cvt_pk_bf16(v1[0], v1[1]); w.w = cvt_pk_bf16(v1[2], v1[3]);
;                     *(GAS u32x4*)(xb + off + bj * HALF) = w;
;                     q += ((v0[0] * v0[0] + v0[1] * v0[1]) + (v0[2] * v0[2] + v0[3] * v0[3])) + ((v1[0] * v1[0] + v1[1] * v1[1]) + (v1[2] * v1[2] + v1[3] * v1[3])); }
;                 q += __shfl_xor(q, 16); q += __shfl_xor(q, 32);
;                 if (fq == 0) rowss[(size_t)row * 16 + u.pn * 4 + wc] = q; }
.LBB0_668:
	s_or_b64 exec, exec, s[22:23]
	v_or_b32_e32 v114, 16, v142
	s_waitcnt lgkmcnt(0)
	v_ashrrev_i32_e32 v115, 31, v114
	v_lshlrev_b64 v[116:117], 11, v[114:115]
	v_lshl_add_u64 v[116:117], s[2:3], 0, v[116:117]
	v_lshl_add_u64 v[120:121], v[140:141], 1, v[116:117]
	s_nop 1
	v_mov_b32_e32 v116, v200
	v_mov_b32_e32 v117, v201
	v_mov_b32_e32 v118, v202
	v_mov_b32_e32 v119, v203
	v_lshlrev_b32_e32 v122, 16, v116
	v_and_b32_e32 v123, 0xffff0000, v116
	v_lshlrev_b32_e32 v116, 16, v117
	v_and_b32_e32 v117, 0xffff0000, v117
	v_pk_add_f32 v[112:113], v[112:113], v[116:117]
	v_lshlrev_b32_e32 v116, 16, v118
	v_and_b32_e32 v117, 0xffff0000, v118
	v_pk_add_f32 v[116:117], v[106:107], v[116:117]
	v_lshlrev_b32_e32 v106, 16, v119
	v_and_b32_e32 v107, 0xffff0000, v119
	v_pk_add_f32 v[110:111], v[110:111], v[122:123]
	v_pk_add_f32 v[118:119], v[108:109], v[106:107]
	v_cvt_pk_bf16_f32 v106, v110, v111
	v_cvt_pk_bf16_f32 v107, v112, v113
	v_cvt_pk_bf16_f32 v108, v116, v117
	v_cvt_pk_bf16_f32 v109, v118, v119
	global_store_dwordx4 v[120:121], v[106:109], off
	s_nop 1
	v_pk_mul_f32 v[106:107], v[110:111], v[110:111]
	v_pk_mul_f32 v[108:109], v[112:113], v[112:113]
	v_pk_mul_f32 v[110:111], v[116:117], v[116:117]
	v_pk_mul_f32 v[112:113], v[118:119], v[118:119]
	s_nop 1
	v_mov_b32_e32 v116, v204
	v_mov_b32_e32 v117, v205
	v_mov_b32_e32 v118, v206
	v_mov_b32_e32 v119, v207
	v_lshlrev_b32_e32 v122, 16, v116
	v_and_b32_e32 v123, 0xffff0000, v116
	v_lshlrev_b32_e32 v116, 16, v117
	v_and_b32_e32 v117, 0xffff0000, v117
	v_pk_add_f32 v[104:105], v[104:105], v[116:117]
	v_lshlrev_b32_e32 v116, 16, v118
	v_and_b32_e32 v117, 0xffff0000, v118
	v_pk_add_f32 v[116:117], v[98:99], v[116:117]
	v_lshlrev_b32_e32 v98, 16, v119
	v_and_b32_e32 v99, 0xffff0000, v119
	v_pk_add_f32 v[102:103], v[102:103], v[122:123]
	v_pk_add_f32 v[118:119], v[100:101], v[98:99]
	v_cvt_pk_bf16_f32 v98, v102, v103
	v_cvt_pk_bf16_f32 v99, v104, v105
	v_cvt_pk_bf16_f32 v100, v116, v117
	v_cvt_pk_bf16_f32 v101, v118, v119
	global_store_dwordx4 v[120:121], v[98:101], off offset:256
	s_nop 1
	v_pk_mul_f32 v[98:99], v[102:103], v[102:103]
	v_pk_mul_f32 v[100:101], v[104:105], v[104:105]
	v_add_f32_e32 v98, v98, v99
	v_add_f32_e32 v100, v100, v101
	v_pk_mul_f32 v[102:103], v[116:117], v[116:117]
	v_pk_mul_f32 v[104:105], v[118:119], v[118:119]
	v_add_f32_e32 v98, v98, v100
	v_add_f32_e32 v99, v112, v113
	v_add_f32_e32 v100, v110, v111
	v_add_f32_e32 v104, v104, v105
	v_add_f32_e32 v102, v102, v103
	v_add_f32_e32 v99, v100, v99
	v_add_f32_e32 v100, v108, v109
	v_add_f32_e32 v101, v106, v107
	v_add_f32_e32 v102, v102, v104
	v_add_f32_e32 v100, v101, v100
	v_add_f32_e32 v98, v98, v102
	v_add_f32_e32 v99, v100, v99
	v_add_f32_e32 v98, v99, v98
	v_mov_b32_e32 v99, v98
	s_nop 1
	v_permlane16_swap_b32_e32 v98, v99
	s_waitcnt lgkmcnt(0)
	v_add_f32_e32 v98, v98, v99
	v_mov_b32_e32 v99, v98
	s_nop 1
	v_permlane32_swap_b32_e32 v98, v99
	s_and_saveexec_b64 s[22:23], s[6:7]
	s_cbranch_execz .LBB0_670
	v_lshlrev_b64 v[100:101], 6, v[114:115]
	v_lshl_add_u64 v[100:101], s[4:5], 0, v[100:101]
	v_lshl_add_u64 v[100:101], s[20:21], 2, v[100:101]
	s_lshl_b32 s72, s42, 2
	v_lshl_add_u64 v[100:101], v[100:101], 0, s[72:73]
	s_waitcnt lgkmcnt(0)
	v_add_f32_e32 v98, v98, v99
	global_store_dword v[100:101], v98, off
.LBB0_670:
	s_or_b64 exec, exec, s[22:23]
	v_or_b32_e32 v98, 32, v142
	s_waitcnt lgkmcnt(0)
	v_ashrrev_i32_e32 v99, 31, v98
	v_lshlrev_b64 v[100:101], 11, v[98:99]
	v_lshl_add_u64 v[100:101], s[2:3], 0, v[100:101]
	v_lshl_add_u64 v[104:105], v[140:141], 1, v[100:101]
	s_nop 1
	v_mov_b32_e32 v100, v208
	v_mov_b32_e32 v101, v209
	v_mov_b32_e32 v102, v210
	v_mov_b32_e32 v103, v211
	v_lshlrev_b32_e32 v106, 16, v100
	v_and_b32_e32 v107, 0xffff0000, v100
	v_lshlrev_b32_e32 v100, 16, v101
	v_and_b32_e32 v101, 0xffff0000, v101
	v_pk_add_f32 v[96:97], v[96:97], v[100:101]
	v_lshlrev_b32_e32 v100, 16, v102
	v_and_b32_e32 v101, 0xffff0000, v102
	v_pk_add_f32 v[100:101], v[90:91], v[100:101]
	v_lshlrev_b32_e32 v90, 16, v103
	v_and_b32_e32 v91, 0xffff0000, v103
	v_pk_add_f32 v[94:95], v[94:95], v[106:107]
	v_pk_add_f32 v[102:103], v[92:93], v[90:91]
	v_cvt_pk_bf16_f32 v90, v94, v95
	v_cvt_pk_bf16_f32 v91, v96, v97
	v_cvt_pk_bf16_f32 v92, v100, v101
	v_cvt_pk_bf16_f32 v93, v102, v103
	global_store_dwordx4 v[104:105], v[90:93], off
	s_nop 1
	v_pk_mul_f32 v[90:91], v[94:95], v[94:95]
	v_pk_mul_f32 v[92:93], v[96:97], v[96:97]
	v_pk_mul_f32 v[94:95], v[100:101], v[100:101]
	v_pk_mul_f32 v[96:97], v[102:103], v[102:103]
	s_nop 1
	v_mov_b32_e32 v100, v212
	v_mov_b32_e32 v101, v213
	v_mov_b32_e32 v102, v214
	v_mov_b32_e32 v103, v215
	v_lshlrev_b32_e32 v106, 16, v100
	v_and_b32_e32 v107, 0xffff0000, v100
	v_lshlrev_b32_e32 v100, 16, v101
	v_and_b32_e32 v101, 0xffff0000, v101
	v_pk_add_f32 v[88:89], v[88:89], v[100:101]
	v_lshlrev_b32_e32 v100, 16, v102
	v_and_b32_e32 v101, 0xffff0000, v102
	v_pk_add_f32 v[100:101], v[82:83], v[100:101]
	v_lshlrev_b32_e32 v82, 16, v103
	v_and_b32_e32 v83, 0xffff0000, v103
	v_pk_add_f32 v[86:87], v[86:87], v[106:107]
	v_pk_add_f32 v[102:103], v[84:85], v[82:83]
	v_cvt_pk_bf16_f32 v82, v86, v87
	v_cvt_pk_bf16_f32 v83, v88, v89
	v_cvt_pk_bf16_f32 v84, v100, v101
	v_cvt_pk_bf16_f32 v85, v102, v103
	global_store_dwordx4 v[104:105], v[82:85], off offset:256
	s_nop 1
	v_pk_mul_f32 v[82:83], v[86:87], v[86:87]
	v_pk_mul_f32 v[84:85], v[88:89], v[88:89]
	v_add_f32_e32 v82, v82, v83
	v_add_f32_e32 v84, v84, v85
	v_pk_mul_f32 v[86:87], v[100:101], v[100:101]
	v_pk_mul_f32 v[88:89], v[102:103], v[102:103]
	v_add_f32_e32 v82, v82, v84
	v_add_f32_e32 v83, v96, v97
	v_add_f32_e32 v84, v94, v95
	v_add_f32_e32 v88, v88, v89
	v_add_f32_e32 v86, v86, v87
	v_add_f32_e32 v83, v84, v83
	v_add_f32_e32 v84, v92, v93
	v_add_f32_e32 v85, v90, v91
	v_add_f32_e32 v86, v86, v88
	v_add_f32_e32 v84, v85, v84
	v_add_f32_e32 v82, v82, v86
	v_add_f32_e32 v83, v84, v83
	v_add_f32_e32 v82, v83, v82
	v_mov_b32_e32 v83, v82
	s_nop 1
	v_permlane16_swap_b32_e32 v82, v83
	s_waitcnt lgkmcnt(0)
	v_add_f32_e32 v82, v82, v83
	v_mov_b32_e32 v83, v82
	s_nop 1
	v_permlane32_swap_b32_e32 v82, v83
	s_and_saveexec_b64 s[22:23], s[6:7]
	s_cbranch_execz .LBB0_672
	v_lshlrev_b64 v[84:85], 6, v[98:99]
	v_lshl_add_u64 v[84:85], s[4:5], 0, v[84:85]
	v_lshl_add_u64 v[84:85], s[20:21], 2, v[84:85]
	s_lshl_b32 s72, s42, 2
	v_lshl_add_u64 v[84:85], v[84:85], 0, s[72:73]
	s_waitcnt lgkmcnt(0)
	v_add_f32_e32 v82, v82, v83
	global_store_dword v[84:85], v82, off
; #define GAS __attribute__((address_space(1)))
; __device__ __forceinline__ unsigned cvt_pk_bf16(float lo, float hi) { f32x2 v = {lo, hi}; bf16x2_t b = __builtin_convertvector(v, bf16x2_t); return __builtin_bit_cast(unsigned, b); }
; __device__ __forceinline__ float bf_lo(unsigned u) { return __uint_as_float(u << 16); }
; __device__ __forceinline__ float bf_hi(unsigned u) { return __uint_as_float(u & 0xffff0000u); }
;     __device__ __forceinline__ void operator()(const f32x4 (&acc)[2][2][4][2], const Unit& u, int wr, int wc, int fr, int fq) const {
;     ...
;             for (int m = 0; m < 4; ++m) { const int row = row0 + ai * HALF + m * 16; const size_t off = (size_t)row * 1024 + col0; float q = 0.f;
; #pragma unroll
;                 for (int bj = 0; bj < 2; ++bj) { const u32x4 xo = *(const GAS u32x4*)(xb + off + bj * HALF);
;                     f32x4 v0 = acc[ai][bj][m][0], v1 = acc[ai][bj][m][1];
;                     v0[0] += bf_lo(xo.x); v0[1] += bf_hi(xo.x); v0[2] += bf_lo(xo.y); v0[3] += bf_hi(xo.y); v1[0] += bf_lo(xo.z); v1[1] += bf_hi(xo.z); v1[2] += bf_lo(xo.w); v1[3] += bf_hi(xo.w);
;                     if (out) { *(GAS f32x4*)(out + off + bj * HALF) = v0; *(GAS f32x4*)(out + off + bj * HALF + 4) = v1; }
;                     u32x4 w; w.x = cvt_pk_bf16(v0[0], v0[1]); w.y = cvt_pk_bf16(v0[2], v0[3]); w.z = cvt_pk_bf16(v1[0], v1[1]); w.w = cvt_pk_bf16(v1[2], v1[3]);
;                     *(GAS u32x4*)(xb + off + bj * HALF) = w;
;                     q += ((v0[0] * v0[0] + v0[1] * v0[1]) + (v0[2] * v0[2] + v0[3] * v0[3])) + ((v1[0] * v1[0] + v1[1] * v1[1]) + (v1[2] * v1[2] + v1[3] * v1[3])); }
;                 q += __shfl_xor(q, 16); q += __shfl_xor(q, 32);
;                 if (fq == 0) rowss[(size_t)row * 16 + u.pn * 4 + wc] = q; }
.LBB0_672:
	s_or_b64 exec, exec, s[22:23]
	v_or_b32_e32 v82, 48, v142
	s_waitcnt lgkmcnt(0)
	v_ashrrev_i32_e32 v83, 31, v82
	v_lshlrev_b64 v[84:85], 11, v[82:83]
	v_lshl_add_u64 v[84:85], s[2:3], 0, v[84:85]
	v_lshl_add_u64 v[88:89], v[140:141], 1, v[84:85]
	s_nop 1
	v_mov_b32_e32 v84, v216
	v_mov_b32_e32 v85, v217
	v_mov_b32_e32 v86, v218
	v_mov_b32_e32 v87, v219
	v_lshlrev_b32_e32 v90, 16, v84
	v_and_b32_e32 v91, 0xffff0000, v84
	v_lshlrev_b32_e32 v84, 16, v85
	v_and_b32_e32 v85, 0xffff0000, v85
	v_pk_add_f32 v[80:81], v[80:81], v[84:85]
	v_lshlrev_b32_e32 v84, 16, v86
	v_and_b32_e32 v85, 0xffff0000, v86
	v_pk_add_f32 v[84:85], v[74:75], v[84:85]
	v_lshlrev_b32_e32 v74, 16, v87
	v_and_b32_e32 v75, 0xffff0000, v87
	v_pk_add_f32 v[78:79], v[78:79], v[90:91]
	v_pk_add_f32 v[86:87], v[76:77], v[74:75]
	v_cvt_pk_bf16_f32 v74, v78, v79
	v_cvt_pk_bf16_f32 v75, v80, v81
	v_cvt_pk_bf16_f32 v76, v84, v85
	v_cvt_pk_bf16_f32 v77, v86, v87
	global_store_dwordx4 v[88:89], v[74:77], off
	s_nop 1
	v_pk_mul_f32 v[74:75], v[78:79], v[78:79]
	v_pk_mul_f32 v[76:77], v[80:81], v[80:81]
	v_pk_mul_f32 v[78:79], v[84:85], v[84:85]
	v_pk_mul_f32 v[80:81], v[86:87], v[86:87]
	s_nop 1
	v_mov_b32_e32 v84, v220
	v_mov_b32_e32 v85, v221
	v_mov_b32_e32 v86, v222
	v_mov_b32_e32 v87, v223
	v_lshlrev_b32_e32 v90, 16, v84
	v_and_b32_e32 v91, 0xffff0000, v84
	v_lshlrev_b32_e32 v84, 16, v85
	v_and_b32_e32 v85, 0xffff0000, v85
	v_pk_add_f32 v[72:73], v[72:73], v[84:85]
	v_lshlrev_b32_e32 v84, 16, v86
	v_and_b32_e32 v85, 0xffff0000, v86
	v_pk_add_f32 v[84:85], v[66:67], v[84:85]
	v_lshlrev_b32_e32 v66, 16, v87
	v_and_b32_e32 v67, 0xffff0000, v87
	v_pk_add_f32 v[70:71], v[70:71], v[90:91]
	v_pk_add_f32 v[86:87], v[68:69], v[66:67]
	v_cvt_pk_bf16_f32 v66, v70, v71
	v_cvt_pk_bf16_f32 v67, v72, v73
	v_cvt_pk_bf16_f32 v68, v84, v85
	v_cvt_pk_bf16_f32 v69, v86, v87
	global_store_dwordx4 v[88:89], v[66:69], off offset:256
	s_nop 1
	v_pk_mul_f32 v[66:67], v[70:71], v[70:71]
	v_pk_mul_f32 v[68:69], v[72:73], v[72:73]
	v_add_f32_e32 v66, v66, v67
	v_add_f32_e32 v68, v68, v69
	v_pk_mul_f32 v[70:71], v[84:85], v[84:85]
	v_pk_mul_f32 v[72:73], v[86:87], v[86:87]
	v_add_f32_e32 v66, v66, v68
	v_add_f32_e32 v67, v80, v81
	v_add_f32_e32 v68, v78, v79
	v_add_f32_e32 v72, v72, v73
	v_add_f32_e32 v70, v70, v71
	v_add_f32_e32 v67, v68, v67
	v_add_f32_e32 v68, v76, v77
	v_add_f32_e32 v69, v74, v75
	v_add_f32_e32 v70, v70, v72
	v_add_f32_e32 v68, v69, v68
	v_add_f32_e32 v66, v66, v70
	v_add_f32_e32 v67, v68, v67
	v_add_f32_e32 v66, v67, v66
	v_mov_b32_e32 v67, v66
	s_nop 1
	v_permlane16_swap_b32_e32 v66, v67
	s_waitcnt lgkmcnt(0)
	v_add_f32_e32 v66, v66, v67
	v_mov_b32_e32 v67, v66
	s_nop 1
	v_permlane32_swap_b32_e32 v66, v67
	s_and_saveexec_b64 s[22:23], s[6:7]
	s_cbranch_execz .LBB0_674
	v_lshlrev_b64 v[68:69], 6, v[82:83]
	v_lshl_add_u64 v[68:69], s[4:5], 0, v[68:69]
	v_lshl_add_u64 v[68:69], s[20:21], 2, v[68:69]
	s_lshl_b32 s72, s42, 2
	v_lshl_add_u64 v[68:69], v[68:69], 0, s[72:73]
	s_waitcnt lgkmcnt(0)
	v_add_f32_e32 v66, v66, v67
	global_store_dword v[68:69], v66, off
.LBB0_674:
	s_or_b64 exec, exec, s[22:23]
	v_add_u32_e32 v66, 0x80, v142
	s_waitcnt lgkmcnt(0)
	v_ashrrev_i32_e32 v67, 31, v66
	v_lshlrev_b64 v[68:69], 11, v[66:67]
	v_lshl_add_u64 v[68:69], s[2:3], 0, v[68:69]
	v_lshl_add_u64 v[72:73], v[140:141], 1, v[68:69]
	v_add_u32_e32 v225, 0x40000, v224
	global_load_dwordx4 v[192:195], v225, s[2:3]
	global_load_dwordx4 v[196:199], v225, s[2:3] offset:256
	v_add_u32_e32 v225, 0x48000, v224
	global_load_dwordx4 v[200:203], v225, s[2:3]
	global_load_dwordx4 v[204:207], v225, s[2:3] offset:256
	v_add_u32_e32 v225, 0x50000, v224
	global_load_dwordx4 v[208:211], v225, s[2:3]
	global_load_dwordx4 v[212:215], v225, s[2:3] offset:256
	v_add_u32_e32 v225, 0x58000, v224
	global_load_dwordx4 v[216:219], v225, s[2:3]
	global_load_dwordx4 v[220:223], v225, s[2:3] offset:256
	s_waitcnt vmcnt(0)
	s_nop 1
	v_mov_b32_e32 v68, v192
	v_mov_b32_e32 v69, v193
	v_mov_b32_e32 v70, v194
	v_mov_b32_e32 v71, v195
	v_lshlrev_b32_e32 v74, 16, v68
	v_and_b32_e32 v75, 0xffff0000, v68
	v_lshlrev_b32_e32 v68, 16, v69
	v_and_b32_e32 v69, 0xffff0000, v69
	v_pk_add_f32 v[64:65], v[64:65], v[68:69]
	v_lshlrev_b32_e32 v68, 16, v70
	v_and_b32_e32 v69, 0xffff0000, v70
	v_pk_add_f32 v[68:69], v[58:59], v[68:69]
	v_lshlrev_b32_e32 v58, 16, v71
	v_and_b32_e32 v59, 0xffff0000, v71
	v_pk_add_f32 v[62:63], v[62:63], v[74:75]
	v_pk_add_f32 v[70:71], v[60:61], v[58:59]
	v_cvt_pk_bf16_f32 v58, v62, v63
	v_cvt_pk_bf16_f32 v59, v64, v65
	v_cvt_pk_bf16_f32 v60, v68, v69
	v_cvt_pk_bf16_f32 v61, v70, v71
	global_store_dwordx4 v[72:73], v[58:61], off
	s_nop 1
	v_pk_mul_f32 v[58:59], v[62:63], v[62:63]
	v_pk_mul_f32 v[60:61], v[64:65], v[64:65]
	v_pk_mul_f32 v[62:63], v[68:69], v[68:69]
	v_pk_mul_f32 v[64:65], v[70:71], v[70:71]
	s_nop 1
	v_mov_b32_e32 v68, v196
	v_mov_b32_e32 v69, v197
	v_mov_b32_e32 v70, v198
	v_mov_b32_e32 v71, v199
	v_lshlrev_b32_e32 v74, 16, v68
	v_and_b32_e32 v75, 0xffff0000, v68
	v_lshlrev_b32_e32 v68, 16, v69
	v_and_b32_e32 v69, 0xffff0000, v69
	v_pk_add_f32 v[56:57], v[56:57], v[68:69]
	v_lshlrev_b32_e32 v68, 16, v70
	v_and_b32_e32 v69, 0xffff0000, v70
	v_pk_add_f32 v[68:69], v[50:51], v[68:69]
	v_lshlrev_b32_e32 v50, 16, v71
	v_and_b32_e32 v51, 0xffff0000, v71
	v_pk_add_f32 v[54:55], v[54:55], v[74:75]
	v_pk_add_f32 v[70:71], v[52:53], v[50:51]
	v_cvt_pk_bf16_f32 v50, v54, v55
	v_cvt_pk_bf16_f32 v51, v56, v57
	v_cvt_pk_bf16_f32 v52, v68, v69
	v_cvt_pk_bf16_f32 v53, v70, v71
	global_store_dwordx4 v[72:73], v[50:53], off offset:256
	s_nop 1
	v_pk_mul_f32 v[50:51], v[54:55], v[54:55]
	v_pk_mul_f32 v[52:53], v[56:57], v[56:57]
	v_add_f32_e32 v50, v50, v51
	v_add_f32_e32 v52, v52, v53
	v_pk_mul_f32 v[54:55], v[68:69], v[68:69]
	v_pk_mul_f32 v[56:57], v[70:71], v[70:71]
	v_add_f32_e32 v50, v50, v52
	v_add_f32_e32 v51, v64, v65
	v_add_f32_e32 v52, v62, v63
	v_add_f32_e32 v56, v56, v57
	v_add_f32_e32 v54, v54, v55
	v_add_f32_e32 v51, v52, v51
	v_add_f32_e32 v52, v60, v61
	v_add_f32_e32 v53, v58, v59
	v_add_f32_e32 v54, v54, v56
	v_add_f32_e32 v52, v53, v52
	v_add_f32_e32 v50, v50, v54
	v_add_f32_e32 v51, v52, v51
	v_add_f32_e32 v50, v51, v50
	v_mov_b32_e32 v51, v50
	s_nop 1
	v_permlane16_swap_b32_e32 v50, v51
	s_waitcnt lgkmcnt(0)
	v_add_f32_e32 v50, v50, v51
	v_mov_b32_e32 v51, v50
	s_nop 1
	v_permlane32_swap_b32_e32 v50, v51
	s_and_saveexec_b64 s[22:23], s[6:7]
	s_cbranch_execz .LBB0_676
	v_lshlrev_b64 v[52:53], 6, v[66:67]
	v_lshl_add_u64 v[52:53], s[4:5], 0, v[52:53]
	v_lshl_add_u64 v[52:53], s[20:21], 2, v[52:53]
	s_lshl_b32 s72, s42, 2
	v_lshl_add_u64 v[52:53], v[52:53], 0, s[72:73]
	s_waitcnt lgkmcnt(0)
	v_add_f32_e32 v50, v50, v51
	global_store_dword v[52:53], v50, off
; #define GAS __attribute__((address_space(1)))
; __device__ __forceinline__ unsigned cvt_pk_bf16(float lo, float hi) { f32x2 v = {lo, hi}; bf16x2_t b = __builtin_convertvector(v, bf16x2_t); return __builtin_bit_cast(unsigned, b); }
; __device__ __forceinline__ float bf_lo(unsigned u) { return __uint_as_float(u << 16); }
; __device__ __forceinline__ float bf_hi(unsigned u) { return __uint_as_float(u & 0xffff0000u); }
;     __device__ __forceinline__ void operator()(const f32x4 (&acc)[2][2][4][2], const Unit& u, int wr, int wc, int fr, int fq) const {
;     ...
;             for (int m = 0; m < 4; ++m) { const int row = row0 + ai * HALF + m * 16; const size_t off = (size_t)row * 1024 + col0; float q = 0.f;
; #pragma unroll
;                 for (int bj = 0; bj < 2; ++bj) { const u32x4 xo = *(const GAS u32x4*)(xb + off + bj * HALF);
;                     f32x4 v0 = acc[ai][bj][m][0], v1 = acc[ai][bj][m][1];
;                     v0[0] += bf_lo(xo.x); v0[1] += bf_hi(xo.x); v0[2] += bf_lo(xo.y); v0[3] += bf_hi(xo.y); v1[0] += bf_lo(xo.z); v1[1] += bf_hi(xo.z); v1[2] += bf_lo(xo.w); v1[3] += bf_hi(xo.w);
;                     if (out) { *(GAS f32x4*)(out + off + bj * HALF) = v0; *(GAS f32x4*)(out + off + bj * HALF + 4) = v1; }
;                     u32x4 w; w.x = cvt_pk_bf16(v0[0], v0[1]); w.y = cvt_pk_bf16(v0[2], v0[3]); w.z = cvt_pk_bf16(v1[0], v1[1]); w.w = cvt_pk_bf16(v1[2], v1[3]);
;                     *(GAS u32x4*)(xb + off + bj * HALF) = w;
;                     q += ((v0[0] * v0[0] + v0[1] * v0[1]) + (v0[2] * v0[2] + v0[3] * v0[3])) + ((v1[0] * v1[0] + v1[1] * v1[1]) + (v1[2] * v1[2] + v1[3] * v1[3])); }
;                 q += __shfl_xor(q, 16); q += __shfl_xor(q, 32);
;                 if (fq == 0) rowss[(size_t)row * 16 + u.pn * 4 + wc] = q; }
.LBB0_676:
	s_or_b64 exec, exec, s[22:23]
	v_add_u32_e32 v50, 0x90, v142
	s_waitcnt lgkmcnt(0)
	v_ashrrev_i32_e32 v51, 31, v50
	v_lshlrev_b64 v[52:53], 11, v[50:51]
	v_lshl_add_u64 v[52:53], s[2:3], 0, v[52:53]
	v_lshl_add_u64 v[56:57], v[140:141], 1, v[52:53]
	s_nop 1
	v_mov_b32_e32 v52, v200
	v_mov_b32_e32 v53, v201
	v_mov_b32_e32 v54, v202
	v_mov_b32_e32 v55, v203
	v_lshlrev_b32_e32 v58, 16, v52
	v_and_b32_e32 v59, 0xffff0000, v52
	v_lshlrev_b32_e32 v52, 16, v53
	v_and_b32_e32 v53, 0xffff0000, v53
	v_pk_add_f32 v[48:49], v[48:49], v[52:53]
	v_lshlrev_b32_e32 v52, 16, v54
	v_and_b32_e32 v53, 0xffff0000, v54
	v_pk_add_f32 v[52:53], v[42:43], v[52:53]
	v_lshlrev_b32_e32 v42, 16, v55
	v_and_b32_e32 v43, 0xffff0000, v55
	v_pk_add_f32 v[46:47], v[46:47], v[58:59]
	v_pk_add_f32 v[54:55], v[44:45], v[42:43]
	v_cvt_pk_bf16_f32 v42, v46, v47
	v_cvt_pk_bf16_f32 v43, v48, v49
	v_cvt_pk_bf16_f32 v44, v52, v53
	v_cvt_pk_bf16_f32 v45, v54, v55
	global_store_dwordx4 v[56:57], v[42:45], off
	s_nop 1
	v_pk_mul_f32 v[42:43], v[46:47], v[46:47]
	v_pk_mul_f32 v[44:45], v[48:49], v[48:49]
	v_pk_mul_f32 v[46:47], v[52:53], v[52:53]
	v_pk_mul_f32 v[48:49], v[54:55], v[54:55]
	s_nop 1
	v_mov_b32_e32 v52, v204
	v_mov_b32_e32 v53, v205
	v_mov_b32_e32 v54, v206
	v_mov_b32_e32 v55, v207
	v_lshlrev_b32_e32 v58, 16, v52
	v_and_b32_e32 v59, 0xffff0000, v52
	v_lshlrev_b32_e32 v52, 16, v53
	v_and_b32_e32 v53, 0xffff0000, v53
	v_pk_add_f32 v[40:41], v[40:41], v[52:53]
	v_lshlrev_b32_e32 v52, 16, v54
	v_and_b32_e32 v53, 0xffff0000, v54
	v_pk_add_f32 v[52:53], v[34:35], v[52:53]
	v_lshlrev_b32_e32 v34, 16, v55
	v_and_b32_e32 v35, 0xffff0000, v55
	v_pk_add_f32 v[38:39], v[38:39], v[58:59]
	v_pk_add_f32 v[54:55], v[36:37], v[34:35]
	v_cvt_pk_bf16_f32 v34, v38, v39
	v_cvt_pk_bf16_f32 v35, v40, v41
	v_cvt_pk_bf16_f32 v36, v52, v53
	v_cvt_pk_bf16_f32 v37, v54, v55
	global_store_dwordx4 v[56:57], v[34:37], off offset:256
	s_nop 1
	v_pk_mul_f32 v[34:35], v[38:39], v[38:39]
	v_pk_mul_f32 v[36:37], v[40:41], v[40:41]
	v_add_f32_e32 v34, v34, v35
	v_add_f32_e32 v36, v36, v37
	v_pk_mul_f32 v[38:39], v[52:53], v[52:53]
	v_pk_mul_f32 v[40:41], v[54:55], v[54:55]
	v_add_f32_e32 v34, v34, v36
	v_add_f32_e32 v35, v48, v49
	v_add_f32_e32 v36, v46, v47
	v_add_f32_e32 v40, v40, v41
	v_add_f32_e32 v38, v38, v39
	v_add_f32_e32 v35, v36, v35
	v_add_f32_e32 v36, v44, v45
	v_add_f32_e32 v37, v42, v43
	v_add_f32_e32 v38, v38, v40
	v_add_f32_e32 v36, v37, v36
	v_add_f32_e32 v34, v34, v38
	v_add_f32_e32 v35, v36, v35
	v_add_f32_e32 v34, v35, v34
	v_mov_b32_e32 v35, v34
	s_nop 1
	v_permlane16_swap_b32_e32 v34, v35
	s_waitcnt lgkmcnt(0)
	v_add_f32_e32 v34, v34, v35
	v_mov_b32_e32 v35, v34
	s_nop 1
	v_permlane32_swap_b32_e32 v34, v35
	s_and_saveexec_b64 s[22:23], s[6:7]
	s_cbranch_execz .LBB0_678
	v_lshlrev_b64 v[36:37], 6, v[50:51]
	v_lshl_add_u64 v[36:37], s[4:5], 0, v[36:37]
	v_lshl_add_u64 v[36:37], s[20:21], 2, v[36:37]
	s_lshl_b32 s72, s42, 2
	v_lshl_add_u64 v[36:37], v[36:37], 0, s[72:73]
	s_waitcnt lgkmcnt(0)
	v_add_f32_e32 v34, v34, v35
	global_store_dword v[36:37], v34, off
; #define GAS __attribute__((address_space(1)))
; __device__ __forceinline__ unsigned cvt_pk_bf16(float lo, float hi) { f32x2 v = {lo, hi}; bf16x2_t b = __builtin_convertvector(v, bf16x2_t); return __builtin_bit_cast(unsigned, b); }
; __device__ __forceinline__ float bf_lo(unsigned u) { return __uint_as_float(u << 16); }
; __device__ __forceinline__ float bf_hi(unsigned u) { return __uint_as_float(u & 0xffff0000u); }
;     __device__ __forceinline__ void operator()(const f32x4 (&acc)[2][2][4][2], const Unit& u, int wr, int wc, int fr, int fq) const {
;     ...
;             for (int m = 0; m < 4; ++m) { const int row = row0 + ai * HALF + m * 16; const size_t off = (size_t)row * 1024 + col0; float q = 0.f;
; #pragma unroll
;                 for (int bj = 0; bj < 2; ++bj) { const u32x4 xo = *(const GAS u32x4*)(xb + off + bj * HALF);
;                     f32x4 v0 = acc[ai][bj][m][0], v1 = acc[ai][bj][m][1];
;                     v0[0] += bf_lo(xo.x); v0[1] += bf_hi(xo.x); v0[2] += bf_lo(xo.y); v0[3] += bf_hi(xo.y); v1[0] += bf_lo(xo.z); v1[1] += bf_hi(xo.z); v1[2] += bf_lo(xo.w); v1[3] += bf_hi(xo.w);
;                     if (out) { *(GAS f32x4*)(out + off + bj * HALF) = v0; *(GAS f32x4*)(out + off + bj * HALF + 4) = v1; }
;                     u32x4 w; w.x = cvt_pk_bf16(v0[0], v0[1]); w.y = cvt_pk_bf16(v0[2], v0[3]); w.z = cvt_pk_bf16(v1[0], v1[1]); w.w = cvt_pk_bf16(v1[2], v1[3]);
;                     *(GAS u32x4*)(xb + off + bj * HALF) = w;
;                     q += ((v0[0] * v0[0] + v0[1] * v0[1]) + (v0[2] * v0[2] + v0[3] * v0[3])) + ((v1[0] * v1[0] + v1[1] * v1[1]) + (v1[2] * v1[2] + v1[3] * v1[3])); }
;                 q += __shfl_xor(q, 16); q += __shfl_xor(q, 32);
;                 if (fq == 0) rowss[(size_t)row * 16 + u.pn * 4 + wc] = q; }
.LBB0_678:
	s_or_b64 exec, exec, s[22:23]
	v_add_u32_e32 v34, 0xa0, v142
	s_waitcnt lgkmcnt(0)
	v_ashrrev_i32_e32 v35, 31, v34
	v_lshlrev_b64 v[36:37], 11, v[34:35]
	v_lshl_add_u64 v[36:37], s[2:3], 0, v[36:37]
	v_lshl_add_u64 v[40:41], v[140:141], 1, v[36:37]
	s_nop 1
	v_mov_b32_e32 v36, v208
	v_mov_b32_e32 v37, v209
	v_mov_b32_e32 v38, v210
	v_mov_b32_e32 v39, v211
	v_lshlrev_b32_e32 v42, 16, v36
	v_and_b32_e32 v43, 0xffff0000, v36
	v_lshlrev_b32_e32 v36, 16, v37
	v_and_b32_e32 v37, 0xffff0000, v37
	v_pk_add_f32 v[32:33], v[32:33], v[36:37]
	v_lshlrev_b32_e32 v36, 16, v38
	v_and_b32_e32 v37, 0xffff0000, v38
	v_pk_add_f32 v[36:37], v[26:27], v[36:37]
	v_lshlrev_b32_e32 v26, 16, v39
	v_and_b32_e32 v27, 0xffff0000, v39
	v_pk_add_f32 v[30:31], v[30:31], v[42:43]
	v_pk_add_f32 v[38:39], v[28:29], v[26:27]
	v_cvt_pk_bf16_f32 v26, v30, v31
	v_cvt_pk_bf16_f32 v27, v32, v33
	v_cvt_pk_bf16_f32 v28, v36, v37
	v_cvt_pk_bf16_f32 v29, v38, v39
	global_store_dwordx4 v[40:41], v[26:29], off
	s_nop 1
	v_pk_mul_f32 v[26:27], v[30:31], v[30:31]
	v_pk_mul_f32 v[28:29], v[32:33], v[32:33]
	v_pk_mul_f32 v[30:31], v[36:37], v[36:37]
	v_pk_mul_f32 v[32:33], v[38:39], v[38:39]
	s_nop 1
	v_mov_b32_e32 v36, v212
	v_mov_b32_e32 v37, v213
	v_mov_b32_e32 v38, v214
	v_mov_b32_e32 v39, v215
	v_lshlrev_b32_e32 v42, 16, v36
	v_and_b32_e32 v43, 0xffff0000, v36
	v_lshlrev_b32_e32 v36, 16, v37
	v_and_b32_e32 v37, 0xffff0000, v37
	v_pk_add_f32 v[24:25], v[24:25], v[36:37]
	v_lshlrev_b32_e32 v36, 16, v38
	v_and_b32_e32 v37, 0xffff0000, v38
	v_pk_add_f32 v[36:37], v[18:19], v[36:37]
	v_lshlrev_b32_e32 v18, 16, v39
	v_and_b32_e32 v19, 0xffff0000, v39
	v_pk_add_f32 v[22:23], v[22:23], v[42:43]
	v_pk_add_f32 v[38:39], v[20:21], v[18:19]
	v_cvt_pk_bf16_f32 v18, v22, v23
	v_cvt_pk_bf16_f32 v19, v24, v25
	v_cvt_pk_bf16_f32 v20, v36, v37
	v_cvt_pk_bf16_f32 v21, v38, v39
	global_store_dwordx4 v[40:41], v[18:21], off offset:256
	s_nop 1
	v_pk_mul_f32 v[18:19], v[22:23], v[22:23]
	v_pk_mul_f32 v[20:21], v[24:25], v[24:25]
	v_add_f32_e32 v18, v18, v19
	v_add_f32_e32 v20, v20, v21
	v_pk_mul_f32 v[22:23], v[36:37], v[36:37]
	v_pk_mul_f32 v[24:25], v[38:39], v[38:39]
	v_add_f32_e32 v18, v18, v20
	v_add_f32_e32 v19, v32, v33
	v_add_f32_e32 v20, v30, v31
	v_add_f32_e32 v24, v24, v25
	v_add_f32_e32 v22, v22, v23
	v_add_f32_e32 v19, v20, v19
	v_add_f32_e32 v20, v28, v29
	v_add_f32_e32 v21, v26, v27
	v_add_f32_e32 v22, v22, v24
	v_add_f32_e32 v20, v21, v20
	v_add_f32_e32 v18, v18, v22
	v_add_f32_e32 v19, v20, v19
	v_add_f32_e32 v18, v19, v18
	v_mov_b32_e32 v19, v18
	s_nop 1
	v_permlane16_swap_b32_e32 v18, v19
	s_waitcnt lgkmcnt(0)
	v_add_f32_e32 v18, v18, v19
	v_mov_b32_e32 v19, v18
	s_nop 1
	v_permlane32_swap_b32_e32 v18, v19
	s_and_saveexec_b64 s[22:23], s[6:7]
	s_cbranch_execz .LBB0_680
	v_lshlrev_b64 v[20:21], 6, v[34:35]
	v_lshl_add_u64 v[20:21], s[4:5], 0, v[20:21]
	v_lshl_add_u64 v[20:21], s[20:21], 2, v[20:21]
	s_lshl_b32 s72, s42, 2
	v_lshl_add_u64 v[20:21], v[20:21], 0, s[72:73]
	s_waitcnt lgkmcnt(0)
	v_add_f32_e32 v18, v18, v19
	global_store_dword v[20:21], v18, off
.LBB0_680:
	s_or_b64 exec, exec, s[22:23]
	v_add_u32_e32 v18, 0xb0, v142
	s_waitcnt lgkmcnt(0)
	v_ashrrev_i32_e32 v19, 31, v18
	v_lshlrev_b64 v[20:21], 11, v[18:19]
	v_lshl_add_u64 v[20:21], s[2:3], 0, v[20:21]
	v_lshl_add_u64 v[24:25], v[140:141], 1, v[20:21]
	s_nop 1
	v_mov_b32_e32 v20, v216
	v_mov_b32_e32 v21, v217
	v_mov_b32_e32 v22, v218
	v_mov_b32_e32 v23, v219
	v_lshlrev_b32_e32 v26, 16, v20
	v_and_b32_e32 v27, 0xffff0000, v20
	v_lshlrev_b32_e32 v20, 16, v21
	v_and_b32_e32 v21, 0xffff0000, v21
	v_pk_add_f32 v[16:17], v[16:17], v[20:21]
	v_lshlrev_b32_e32 v20, 16, v22
	v_and_b32_e32 v21, 0xffff0000, v22
	v_pk_add_f32 v[20:21], v[10:11], v[20:21]
	v_lshlrev_b32_e32 v10, 16, v23
	v_and_b32_e32 v11, 0xffff0000, v23
	v_pk_add_f32 v[14:15], v[14:15], v[26:27]
	v_pk_add_f32 v[22:23], v[12:13], v[10:11]
	v_cvt_pk_bf16_f32 v10, v14, v15
	v_cvt_pk_bf16_f32 v11, v16, v17
	v_cvt_pk_bf16_f32 v12, v20, v21
	v_cvt_pk_bf16_f32 v13, v22, v23
	global_store_dwordx4 v[24:25], v[10:13], off
	s_nop 1
	v_pk_mul_f32 v[10:11], v[14:15], v[14:15]
	v_pk_mul_f32 v[12:13], v[16:17], v[16:17]
	v_pk_mul_f32 v[14:15], v[20:21], v[20:21]
	v_pk_mul_f32 v[16:17], v[22:23], v[22:23]
	s_nop 1
	v_mov_b32_e32 v20, v220
	v_mov_b32_e32 v21, v221
	v_mov_b32_e32 v22, v222
	v_mov_b32_e32 v23, v223
	v_lshlrev_b32_e32 v26, 16, v20
	v_and_b32_e32 v27, 0xffff0000, v20
	v_lshlrev_b32_e32 v20, 16, v21
	v_and_b32_e32 v21, 0xffff0000, v21
	v_pk_add_f32 v[8:9], v[8:9], v[20:21]
	v_lshlrev_b32_e32 v20, 16, v22
	v_and_b32_e32 v21, 0xffff0000, v22
	v_pk_add_f32 v[20:21], v[2:3], v[20:21]
	v_lshlrev_b32_e32 v2, 16, v23
	v_and_b32_e32 v3, 0xffff0000, v23
	v_pk_add_f32 v[6:7], v[6:7], v[26:27]
	v_pk_add_f32 v[22:23], v[4:5], v[2:3]
	v_cvt_pk_bf16_f32 v2, v6, v7
	v_cvt_pk_bf16_f32 v3, v8, v9
	v_cvt_pk_bf16_f32 v4, v20, v21
	v_cvt_pk_bf16_f32 v5, v22, v23
	global_store_dwordx4 v[24:25], v[2:5], off offset:256
	s_nop 1
	v_pk_mul_f32 v[2:3], v[6:7], v[6:7]
	v_pk_mul_f32 v[4:5], v[8:9], v[8:9]
	v_add_f32_e32 v2, v2, v3
	v_add_f32_e32 v4, v4, v5
	v_pk_mul_f32 v[6:7], v[20:21], v[20:21]
	v_pk_mul_f32 v[8:9], v[22:23], v[22:23]
	v_add_f32_e32 v2, v2, v4
	v_add_f32_e32 v3, v16, v17
	v_add_f32_e32 v4, v14, v15
	v_add_f32_e32 v8, v8, v9
	v_add_f32_e32 v6, v6, v7
	v_add_f32_e32 v3, v4, v3
	v_add_f32_e32 v4, v12, v13
	v_add_f32_e32 v5, v10, v11
	v_add_f32_e32 v6, v6, v8
	v_add_f32_e32 v4, v5, v4
	v_add_f32_e32 v2, v2, v6
	v_add_f32_e32 v3, v4, v3
	v_add_f32_e32 v2, v3, v2
	v_mov_b32_e32 v3, v2
	s_nop 1
	v_permlane16_swap_b32_e32 v2, v3
	s_waitcnt lgkmcnt(0)
	v_add_f32_e32 v2, v2, v3
	v_mov_b32_e32 v3, v2
	s_nop 1
	v_permlane32_swap_b32_e32 v2, v3
	s_and_saveexec_b64 s[22:23], s[6:7]
	s_cbranch_execz .LBB0_682
	v_lshlrev_b64 v[4:5], 6, v[18:19]
	v_lshl_add_u64 v[4:5], s[4:5], 0, v[4:5]
	v_lshl_add_u64 v[4:5], s[20:21], 2, v[4:5]
	s_lshl_b32 s72, s42, 2
	v_lshl_add_u64 v[4:5], v[4:5], 0, s[72:73]
	s_waitcnt lgkmcnt(0)
	v_add_f32_e32 v2, v2, v3
	global_store_dword v[4:5], v2, off

; #define GAS __attribute__((address_space(1)))
; __device__ __forceinline__ unsigned cvt_pk_bf16(float lo, float hi) { f32x2 v = {lo, hi}; bf16x2_t b = __builtin_convertvector(v, bf16x2_t); return __builtin_bit_cast(unsigned, b); }
; __device__ __forceinline__ float bf_lo(unsigned u) { return __uint_as_float(u << 16); }
; __device__ __forceinline__ float bf_hi(unsigned u) { return __uint_as_float(u & 0xffff0000u); }
;     __device__ __forceinline__ void operator()(const f32x4 (&acc)[2][2][4][2], const Unit& u, int wr, int wc, int fr, int fq) const {
;     ...
;             for (int m = 0; m < 4; ++m) { const int row = row0 + ai * HALF + m * 16; const size_t off = (size_t)row * 1024 + col0; float q = 0.f;
; #pragma unroll
;                 for (int bj = 0; bj < 2; ++bj) { const u32x4 xo = *(const GAS u32x4*)(xb + off + bj * HALF);
;                     f32x4 v0 = acc[ai][bj][m][0], v1 = acc[ai][bj][m][1];
;                     v0[0] += bf_lo(xo.x); v0[1] += bf_hi(xo.x); v0[2] += bf_lo(xo.y); v0[3] += bf_hi(xo.y); v1[0] += bf_lo(xo.z); v1[1] += bf_hi(xo.z); v1[2] += bf_lo(xo.w); v1[3] += bf_hi(xo.w);
;                     if (out) { *(GAS f32x4*)(out + off + bj * HALF) = v0; *(GAS f32x4*)(out + off + bj * HALF + 4) = v1; }
;                     u32x4 w; w.x = cvt_pk_bf16(v0[0], v0[1]); w.y = cvt_pk_bf16(v0[2], v0[3]); w.z = cvt_pk_bf16(v1[0], v1[1]); w.w = cvt_pk_bf16(v1[2], v1[3]);
;                     *(GAS u32x4*)(xb + off + bj * HALF) = w;
;                     q += ((v0[0] * v0[0] + v0[1] * v0[1]) + (v0[2] * v0[2] + v0[3] * v0[3])) + ((v1[0] * v1[0] + v1[1] * v1[1]) + (v1[2] * v1[2] + v1[3] * v1[3])); }
;                 q += __shfl_xor(q, 16); q += __shfl_xor(q, 32);
;                 if (fq == 0) rowss[(size_t)row * 16 + u.pn * 4 + wc] = q; }
.LBB0_846:
	v_pk_mul_f32 v[152:153], v[122:123], v[122:123]
	v_and_b32_e32 v123, 64, v240
	v_pk_mul_f32 v[154:155], v[124:125], v[124:125]
	v_xor_b32_e32 v122, 16, v240
	v_add_u32_e32 v124, 64, v123
	v_cmp_lt_i32_e32 vcc, v122, v124
	v_pk_mul_f32 v[146:147], v[126:127], v[126:127]
	v_cvt_pk_bf16_f32 v126, v114, v115
	v_cndmask_b32_e32 v122, v240, v122, vcc
	v_lshlrev_b32_e32 v123, 2, v122
	v_xor_b32_e32 v122, 32, v240
	v_cvt_pk_bf16_f32 v127, v116, v117
	v_pk_mul_f32 v[114:115], v[114:115], v[114:115]
	v_pk_mul_f32 v[116:117], v[116:117], v[116:117]
	v_cmp_lt_i32_e32 vcc, v122, v124
	v_cvt_pk_bf16_f32 v124, v118, v119
	v_cvt_pk_bf16_f32 v125, v120, v121
	v_pk_mul_f32 v[118:119], v[118:119], v[118:119]
	v_pk_mul_f32 v[120:121], v[120:121], v[120:121]
	v_add_f32_e32 v116, v116, v117
	v_add_f32_e32 v114, v114, v115
	v_add_f32_e32 v114, v114, v116
	v_add_f32_e32 v115, v120, v121
	v_add_f32_e32 v116, v118, v119
	v_add_f32_e32 v115, v116, v115
	v_pk_mul_f32 v[128:129], v[128:129], v[128:129]
	v_add_f32_e32 v114, v115, v114
	v_add_f32_e32 v115, v154, v155
	v_add_f32_e32 v116, v152, v153
	v_add_f32_e32 v115, v116, v115
	v_add_f32_e32 v116, v128, v129
	v_add_f32_e32 v117, v146, v147
	v_add_f32_e32 v116, v117, v116
	v_add_f32_e32 v115, v116, v115
	v_add_f32_e32 v114, v115, v114
	v_mov_b32_e32 v115, v114
	s_nop 1
	v_permlane16_swap_b32_e32 v114, v115
	v_cndmask_b32_e32 v122, v240, v122, vcc
	v_lshlrev_b32_e32 v122, 2, v122
	s_lshl_b32 s22, s48, 2
	s_ashr_i32 s23, s22, 31
	s_waitcnt lgkmcnt(0)
	v_add_f32_e32 v114, v114, v115
	v_mov_b32_e32 v115, v114
	s_nop 1
	v_permlane32_swap_b32_e32 v114, v115
	global_store_dwordx4 v[144:145], v[124:127], off offset:256
	s_and_saveexec_b64 s[24:25], s[6:7]
	s_cbranch_execz .LBB0_848
	v_lshlrev_b64 v[116:117], 6, v[142:143]
	v_lshl_add_u64 v[116:117], s[14:15], 0, v[116:117]
	v_lshl_add_u64 v[116:117], s[22:23], 2, v[116:117]
	s_lshl_b32 s72, s40, 2
	v_lshl_add_u64 v[116:117], v[116:117], 0, s[72:73]
	s_waitcnt lgkmcnt(0)
	v_add_f32_e32 v114, v114, v115
	global_store_dword v[116:117], v114, off

; #define GAS __attribute__((address_space(1)))
; __device__ __forceinline__ unsigned cvt_pk_bf16(float lo, float hi) { f32x2 v = {lo, hi}; bf16x2_t b = __builtin_convertvector(v, bf16x2_t); return __builtin_bit_cast(unsigned, b); }
; __device__ __forceinline__ float bf_lo(unsigned u) { return __uint_as_float(u << 16); }
; __device__ __forceinline__ float bf_hi(unsigned u) { return __uint_as_float(u & 0xffff0000u); }
;     __device__ __forceinline__ void operator()(const f32x4 (&acc)[2][2][4][2], const Unit& u, int wr, int wc, int fr, int fq) const {
;     ...
;                 for (int bj = 0; bj < 2; ++bj) { const u32x4 xo = *(const GAS u32x4*)(xb + off + bj * HALF);
;                     f32x4 v0 = acc[ai][bj][m][0], v1 = acc[ai][bj][m][1];
;                     v0[0] += bf_lo(xo.x); v0[1] += bf_hi(xo.x); v0[2] += bf_lo(xo.y); v0[3] += bf_hi(xo.y); v1[0] += bf_lo(xo.z); v1[1] += bf_hi(xo.z); v1[2] += bf_lo(xo.w); v1[3] += bf_hi(xo.w);
;                     if (out) { *(GAS f32x4*)(out + off + bj * HALF) = v0; *(GAS f32x4*)(out + off + bj * HALF + 4) = v1; }
;                     u32x4 w; w.x = cvt_pk_bf16(v0[0], v0[1]); w.y = cvt_pk_bf16(v0[2], v0[3]); w.z = cvt_pk_bf16(v1[0], v1[1]); w.w = cvt_pk_bf16(v1[2], v1[3]);
;                     *(GAS u32x4*)(xb + off + bj * HALF) = w;
;                     q += ((v0[0] * v0[0] + v0[1] * v0[1]) + (v0[2] * v0[2] + v0[3] * v0[3])) + ((v1[0] * v1[0] + v1[1] * v1[1]) + (v1[2] * v1[2] + v1[3] * v1[3])); }
;                 q += __shfl_xor(q, 16); q += __shfl_xor(q, 32);
;                 if (fq == 0) rowss[(size_t)row * 16 + u.pn * 4 + wc] = q; }
.LBB0_852:
	v_pk_mul_f32 v[120:121], v[108:109], v[108:109]
	v_cvt_pk_bf16_f32 v108, v98, v99
	v_cvt_pk_bf16_f32 v109, v100, v101
	v_pk_mul_f32 v[98:99], v[98:99], v[98:99]
	v_pk_mul_f32 v[100:101], v[100:101], v[100:101]
	v_pk_mul_f32 v[118:119], v[106:107], v[106:107]
	v_cvt_pk_bf16_f32 v106, v102, v103
	v_cvt_pk_bf16_f32 v107, v104, v105
	v_pk_mul_f32 v[102:103], v[102:103], v[102:103]
	v_pk_mul_f32 v[104:105], v[104:105], v[104:105]
	v_add_f32_e32 v100, v100, v101
	v_add_f32_e32 v98, v98, v99
	v_add_f32_e32 v98, v98, v100
	v_add_f32_e32 v99, v104, v105
	v_add_f32_e32 v100, v102, v103
	v_add_f32_e32 v99, v100, v99
	v_pk_mul_f32 v[110:111], v[110:111], v[110:111]
	v_pk_mul_f32 v[112:113], v[112:113], v[112:113]
	v_add_f32_e32 v98, v99, v98
	v_add_f32_e32 v99, v120, v121
	v_add_f32_e32 v100, v118, v119
	v_add_f32_e32 v99, v100, v99
	v_add_f32_e32 v100, v112, v113
	v_add_f32_e32 v101, v110, v111
	v_add_f32_e32 v100, v101, v100
	v_add_f32_e32 v99, v100, v99
	v_add_f32_e32 v98, v99, v98
	v_mov_b32_e32 v99, v98
	s_nop 1
	v_permlane16_swap_b32_e32 v98, v99
	global_store_dwordx4 v[116:117], v[106:109], off offset:256
	s_waitcnt lgkmcnt(0)
	v_add_f32_e32 v98, v98, v99
	v_mov_b32_e32 v99, v98
	s_nop 1
	v_permlane32_swap_b32_e32 v98, v99
	s_and_saveexec_b64 s[24:25], s[6:7]
	s_cbranch_execz .LBB0_854
	v_lshlrev_b64 v[100:101], 6, v[114:115]
	v_lshl_add_u64 v[100:101], s[14:15], 0, v[100:101]
	v_lshl_add_u64 v[100:101], s[22:23], 2, v[100:101]
	s_lshl_b32 s72, s40, 2
	v_lshl_add_u64 v[100:101], v[100:101], 0, s[72:73]
	s_waitcnt lgkmcnt(0)
	v_add_f32_e32 v98, v98, v99
	global_store_dword v[100:101], v98, off

; #define GAS __attribute__((address_space(1)))
; __device__ __forceinline__ unsigned cvt_pk_bf16(float lo, float hi) { f32x2 v = {lo, hi}; bf16x2_t b = __builtin_convertvector(v, bf16x2_t); return __builtin_bit_cast(unsigned, b); }
; __device__ __forceinline__ float bf_lo(unsigned u) { return __uint_as_float(u << 16); }
; __device__ __forceinline__ float bf_hi(unsigned u) { return __uint_as_float(u & 0xffff0000u); }
;     __device__ __forceinline__ void operator()(const f32x4 (&acc)[2][2][4][2], const Unit& u, int wr, int wc, int fr, int fq) const {
;     ...
;                 for (int bj = 0; bj < 2; ++bj) { const u32x4 xo = *(const GAS u32x4*)(xb + off + bj * HALF);
;                     f32x4 v0 = acc[ai][bj][m][0], v1 = acc[ai][bj][m][1];
;                     v0[0] += bf_lo(xo.x); v0[1] += bf_hi(xo.x); v0[2] += bf_lo(xo.y); v0[3] += bf_hi(xo.y); v1[0] += bf_lo(xo.z); v1[1] += bf_hi(xo.z); v1[2] += bf_lo(xo.w); v1[3] += bf_hi(xo.w);
;                     if (out) { *(GAS f32x4*)(out + off + bj * HALF) = v0; *(GAS f32x4*)(out + off + bj * HALF + 4) = v1; }
;                     u32x4 w; w.x = cvt_pk_bf16(v0[0], v0[1]); w.y = cvt_pk_bf16(v0[2], v0[3]); w.z = cvt_pk_bf16(v1[0], v1[1]); w.w = cvt_pk_bf16(v1[2], v1[3]);
;                     *(GAS u32x4*)(xb + off + bj * HALF) = w;
;                     q += ((v0[0] * v0[0] + v0[1] * v0[1]) + (v0[2] * v0[2] + v0[3] * v0[3])) + ((v1[0] * v1[0] + v1[1] * v1[1]) + (v1[2] * v1[2] + v1[3] * v1[3])); }
;                 q += __shfl_xor(q, 16); q += __shfl_xor(q, 32);
;                 if (fq == 0) rowss[(size_t)row * 16 + u.pn * 4 + wc] = q; }
.LBB0_858:
	v_pk_mul_f32 v[104:105], v[92:93], v[92:93]
	v_cvt_pk_bf16_f32 v92, v82, v83
	v_cvt_pk_bf16_f32 v93, v84, v85
	v_pk_mul_f32 v[82:83], v[82:83], v[82:83]
	v_pk_mul_f32 v[84:85], v[84:85], v[84:85]
	v_pk_mul_f32 v[102:103], v[90:91], v[90:91]
	v_cvt_pk_bf16_f32 v90, v86, v87
	v_cvt_pk_bf16_f32 v91, v88, v89
	v_pk_mul_f32 v[86:87], v[86:87], v[86:87]
	v_pk_mul_f32 v[88:89], v[88:89], v[88:89]
	v_add_f32_e32 v84, v84, v85
	v_add_f32_e32 v82, v82, v83
	v_add_f32_e32 v82, v82, v84
	v_add_f32_e32 v83, v88, v89
	v_add_f32_e32 v84, v86, v87
	v_add_f32_e32 v83, v84, v83
	v_pk_mul_f32 v[94:95], v[94:95], v[94:95]
	v_pk_mul_f32 v[96:97], v[96:97], v[96:97]
	v_add_f32_e32 v82, v83, v82
	v_add_f32_e32 v83, v104, v105
	v_add_f32_e32 v84, v102, v103
	v_add_f32_e32 v83, v84, v83
	v_add_f32_e32 v84, v96, v97
	v_add_f32_e32 v85, v94, v95
	v_add_f32_e32 v84, v85, v84
	v_add_f32_e32 v83, v84, v83
	v_add_f32_e32 v82, v83, v82
	v_mov_b32_e32 v83, v82
	s_nop 1
	v_permlane16_swap_b32_e32 v82, v83
	global_store_dwordx4 v[100:101], v[90:93], off offset:256
	s_waitcnt lgkmcnt(0)
	v_add_f32_e32 v82, v82, v83
	v_mov_b32_e32 v83, v82
	s_nop 1
	v_permlane32_swap_b32_e32 v82, v83
	s_and_saveexec_b64 s[24:25], s[6:7]
	s_cbranch_execz .LBB0_860
	v_lshlrev_b64 v[84:85], 6, v[98:99]
	v_lshl_add_u64 v[84:85], s[14:15], 0, v[84:85]
	v_lshl_add_u64 v[84:85], s[22:23], 2, v[84:85]
	s_lshl_b32 s72, s40, 2
	v_lshl_add_u64 v[84:85], v[84:85], 0, s[72:73]
	s_waitcnt lgkmcnt(0)
	v_add_f32_e32 v82, v82, v83
	global_store_dword v[84:85], v82, off

; #define GAS __attribute__((address_space(1)))
; __device__ __forceinline__ unsigned cvt_pk_bf16(float lo, float hi) { f32x2 v = {lo, hi}; bf16x2_t b = __builtin_convertvector(v, bf16x2_t); return __builtin_bit_cast(unsigned, b); }
; __device__ __forceinline__ float bf_lo(unsigned u) { return __uint_as_float(u << 16); }
; __device__ __forceinline__ float bf_hi(unsigned u) { return __uint_as_float(u & 0xffff0000u); }
;     __device__ __forceinline__ void operator()(const f32x4 (&acc)[2][2][4][2], const Unit& u, int wr, int wc, int fr, int fq) const {
;     ...
;                 for (int bj = 0; bj < 2; ++bj) { const u32x4 xo = *(const GAS u32x4*)(xb + off + bj * HALF);
;                     f32x4 v0 = acc[ai][bj][m][0], v1 = acc[ai][bj][m][1];
;                     v0[0] += bf_lo(xo.x); v0[1] += bf_hi(xo.x); v0[2] += bf_lo(xo.y); v0[3] += bf_hi(xo.y); v1[0] += bf_lo(xo.z); v1[1] += bf_hi(xo.z); v1[2] += bf_lo(xo.w); v1[3] += bf_hi(xo.w);
;                     if (out) { *(GAS f32x4*)(out + off + bj * HALF) = v0; *(GAS f32x4*)(out + off + bj * HALF + 4) = v1; }
;                     u32x4 w; w.x = cvt_pk_bf16(v0[0], v0[1]); w.y = cvt_pk_bf16(v0[2], v0[3]); w.z = cvt_pk_bf16(v1[0], v1[1]); w.w = cvt_pk_bf16(v1[2], v1[3]);
;                     *(GAS u32x4*)(xb + off + bj * HALF) = w;
;                     q += ((v0[0] * v0[0] + v0[1] * v0[1]) + (v0[2] * v0[2] + v0[3] * v0[3])) + ((v1[0] * v1[0] + v1[1] * v1[1]) + (v1[2] * v1[2] + v1[3] * v1[3])); }
;                 q += __shfl_xor(q, 16); q += __shfl_xor(q, 32);
;                 if (fq == 0) rowss[(size_t)row * 16 + u.pn * 4 + wc] = q; }
.LBB0_864:
	v_pk_mul_f32 v[88:89], v[76:77], v[76:77]
	v_cvt_pk_bf16_f32 v76, v66, v67
	v_cvt_pk_bf16_f32 v77, v68, v69
	v_pk_mul_f32 v[66:67], v[66:67], v[66:67]
	v_pk_mul_f32 v[68:69], v[68:69], v[68:69]
	v_pk_mul_f32 v[86:87], v[74:75], v[74:75]
	v_cvt_pk_bf16_f32 v74, v70, v71
	v_cvt_pk_bf16_f32 v75, v72, v73
	v_pk_mul_f32 v[70:71], v[70:71], v[70:71]
	v_pk_mul_f32 v[72:73], v[72:73], v[72:73]
	v_add_f32_e32 v68, v68, v69
	v_add_f32_e32 v66, v66, v67
	v_add_f32_e32 v66, v66, v68
	v_add_f32_e32 v67, v72, v73
	v_add_f32_e32 v68, v70, v71
	v_add_f32_e32 v67, v68, v67
	v_pk_mul_f32 v[78:79], v[78:79], v[78:79]
	v_pk_mul_f32 v[80:81], v[80:81], v[80:81]
	v_add_f32_e32 v66, v67, v66
	v_add_f32_e32 v67, v88, v89
	v_add_f32_e32 v68, v86, v87
	v_add_f32_e32 v67, v68, v67
	v_add_f32_e32 v68, v80, v81
	v_add_f32_e32 v69, v78, v79
	v_add_f32_e32 v68, v69, v68
	v_add_f32_e32 v67, v68, v67
	v_add_f32_e32 v66, v67, v66
	v_mov_b32_e32 v67, v66
	s_nop 1
	v_permlane16_swap_b32_e32 v66, v67
	global_store_dwordx4 v[84:85], v[74:77], off offset:256
	s_waitcnt lgkmcnt(0)
	v_add_f32_e32 v66, v66, v67
	v_mov_b32_e32 v67, v66
	s_nop 1
	v_permlane32_swap_b32_e32 v66, v67
	s_and_saveexec_b64 s[24:25], s[6:7]
	s_cbranch_execz .LBB0_866
	v_lshlrev_b64 v[68:69], 6, v[82:83]
	v_lshl_add_u64 v[68:69], s[14:15], 0, v[68:69]
	v_lshl_add_u64 v[68:69], s[22:23], 2, v[68:69]
	s_lshl_b32 s72, s40, 2
	v_lshl_add_u64 v[68:69], v[68:69], 0, s[72:73]
	s_waitcnt lgkmcnt(0)
	v_add_f32_e32 v66, v66, v67
	global_store_dword v[68:69], v66, off

; #define GAS __attribute__((address_space(1)))
; __device__ __forceinline__ unsigned cvt_pk_bf16(float lo, float hi) { f32x2 v = {lo, hi}; bf16x2_t b = __builtin_convertvector(v, bf16x2_t); return __builtin_bit_cast(unsigned, b); }
; __device__ __forceinline__ float bf_lo(unsigned u) { return __uint_as_float(u << 16); }
; __device__ __forceinline__ float bf_hi(unsigned u) { return __uint_as_float(u & 0xffff0000u); }
;     __device__ __forceinline__ void operator()(const f32x4 (&acc)[2][2][4][2], const Unit& u, int wr, int wc, int fr, int fq) const {
;     ...
;                 for (int bj = 0; bj < 2; ++bj) { const u32x4 xo = *(const GAS u32x4*)(xb + off + bj * HALF);
;                     f32x4 v0 = acc[ai][bj][m][0], v1 = acc[ai][bj][m][1];
;                     v0[0] += bf_lo(xo.x); v0[1] += bf_hi(xo.x); v0[2] += bf_lo(xo.y); v0[3] += bf_hi(xo.y); v1[0] += bf_lo(xo.z); v1[1] += bf_hi(xo.z); v1[2] += bf_lo(xo.w); v1[3] += bf_hi(xo.w);
;                     if (out) { *(GAS f32x4*)(out + off + bj * HALF) = v0; *(GAS f32x4*)(out + off + bj * HALF + 4) = v1; }
;                     u32x4 w; w.x = cvt_pk_bf16(v0[0], v0[1]); w.y = cvt_pk_bf16(v0[2], v0[3]); w.z = cvt_pk_bf16(v1[0], v1[1]); w.w = cvt_pk_bf16(v1[2], v1[3]);
;                     *(GAS u32x4*)(xb + off + bj * HALF) = w;
;                     q += ((v0[0] * v0[0] + v0[1] * v0[1]) + (v0[2] * v0[2] + v0[3] * v0[3])) + ((v1[0] * v1[0] + v1[1] * v1[1]) + (v1[2] * v1[2] + v1[3] * v1[3])); }
;                 q += __shfl_xor(q, 16); q += __shfl_xor(q, 32);
;                 if (fq == 0) rowss[(size_t)row * 16 + u.pn * 4 + wc] = q; }
.LBB0_870:
	v_pk_mul_f32 v[72:73], v[60:61], v[60:61]
	v_cvt_pk_bf16_f32 v60, v50, v51
	v_cvt_pk_bf16_f32 v61, v52, v53
	v_pk_mul_f32 v[50:51], v[50:51], v[50:51]
	v_pk_mul_f32 v[52:53], v[52:53], v[52:53]
	v_pk_mul_f32 v[70:71], v[58:59], v[58:59]
	v_cvt_pk_bf16_f32 v58, v54, v55
	v_cvt_pk_bf16_f32 v59, v56, v57
	v_pk_mul_f32 v[54:55], v[54:55], v[54:55]
	v_pk_mul_f32 v[56:57], v[56:57], v[56:57]
	v_add_f32_e32 v52, v52, v53
	v_add_f32_e32 v50, v50, v51
	v_add_f32_e32 v50, v50, v52
	v_add_f32_e32 v51, v56, v57
	v_add_f32_e32 v52, v54, v55
	v_add_f32_e32 v51, v52, v51
	v_pk_mul_f32 v[62:63], v[62:63], v[62:63]
	v_pk_mul_f32 v[64:65], v[64:65], v[64:65]
	v_add_f32_e32 v50, v51, v50
	v_add_f32_e32 v51, v72, v73
	v_add_f32_e32 v52, v70, v71
	v_add_f32_e32 v51, v52, v51
	v_add_f32_e32 v52, v64, v65
	v_add_f32_e32 v53, v62, v63
	v_add_f32_e32 v52, v53, v52
	v_add_f32_e32 v51, v52, v51
	v_add_f32_e32 v50, v51, v50
	v_mov_b32_e32 v51, v50
	s_nop 1
	v_permlane16_swap_b32_e32 v50, v51
	global_store_dwordx4 v[68:69], v[58:61], off offset:256
	s_waitcnt lgkmcnt(0)
	v_add_f32_e32 v50, v50, v51
	v_mov_b32_e32 v51, v50
	s_nop 1
	v_permlane32_swap_b32_e32 v50, v51
	s_and_saveexec_b64 s[24:25], s[6:7]
	s_cbranch_execz .LBB0_872
	v_lshlrev_b64 v[52:53], 6, v[66:67]
	v_lshl_add_u64 v[52:53], s[14:15], 0, v[52:53]
	v_lshl_add_u64 v[52:53], s[22:23], 2, v[52:53]
	s_lshl_b32 s72, s40, 2
	v_lshl_add_u64 v[52:53], v[52:53], 0, s[72:73]
	s_waitcnt lgkmcnt(0)
	v_add_f32_e32 v50, v50, v51
	global_store_dword v[52:53], v50, off

; #define GAS __attribute__((address_space(1)))
; __device__ __forceinline__ unsigned cvt_pk_bf16(float lo, float hi) { f32x2 v = {lo, hi}; bf16x2_t b = __builtin_convertvector(v, bf16x2_t); return __builtin_bit_cast(unsigned, b); }
; __device__ __forceinline__ float bf_lo(unsigned u) { return __uint_as_float(u << 16); }
; __device__ __forceinline__ float bf_hi(unsigned u) { return __uint_as_float(u & 0xffff0000u); }
;     __device__ __forceinline__ void operator()(const f32x4 (&acc)[2][2][4][2], const Unit& u, int wr, int wc, int fr, int fq) const {
;     ...
;                 for (int bj = 0; bj < 2; ++bj) { const u32x4 xo = *(const GAS u32x4*)(xb + off + bj * HALF);
;                     f32x4 v0 = acc[ai][bj][m][0], v1 = acc[ai][bj][m][1];
;                     v0[0] += bf_lo(xo.x); v0[1] += bf_hi(xo.x); v0[2] += bf_lo(xo.y); v0[3] += bf_hi(xo.y); v1[0] += bf_lo(xo.z); v1[1] += bf_hi(xo.z); v1[2] += bf_lo(xo.w); v1[3] += bf_hi(xo.w);
;                     if (out) { *(GAS f32x4*)(out + off + bj * HALF) = v0; *(GAS f32x4*)(out + off + bj * HALF + 4) = v1; }
;                     u32x4 w; w.x = cvt_pk_bf16(v0[0], v0[1]); w.y = cvt_pk_bf16(v0[2], v0[3]); w.z = cvt_pk_bf16(v1[0], v1[1]); w.w = cvt_pk_bf16(v1[2], v1[3]);
;                     *(GAS u32x4*)(xb + off + bj * HALF) = w;
;                     q += ((v0[0] * v0[0] + v0[1] * v0[1]) + (v0[2] * v0[2] + v0[3] * v0[3])) + ((v1[0] * v1[0] + v1[1] * v1[1]) + (v1[2] * v1[2] + v1[3] * v1[3])); }
;                 q += __shfl_xor(q, 16); q += __shfl_xor(q, 32);
;                 if (fq == 0) rowss[(size_t)row * 16 + u.pn * 4 + wc] = q; }
.LBB0_876:
	v_pk_mul_f32 v[56:57], v[44:45], v[44:45]
	v_cvt_pk_bf16_f32 v44, v34, v35
	v_cvt_pk_bf16_f32 v45, v36, v37
	v_pk_mul_f32 v[34:35], v[34:35], v[34:35]
	v_pk_mul_f32 v[36:37], v[36:37], v[36:37]
	v_pk_mul_f32 v[54:55], v[42:43], v[42:43]
	v_cvt_pk_bf16_f32 v42, v38, v39
	v_cvt_pk_bf16_f32 v43, v40, v41
	v_pk_mul_f32 v[38:39], v[38:39], v[38:39]
	v_pk_mul_f32 v[40:41], v[40:41], v[40:41]
	v_add_f32_e32 v36, v36, v37
	v_add_f32_e32 v34, v34, v35
	v_add_f32_e32 v34, v34, v36
	v_add_f32_e32 v35, v40, v41
	v_add_f32_e32 v36, v38, v39
	v_add_f32_e32 v35, v36, v35
	v_pk_mul_f32 v[46:47], v[46:47], v[46:47]
	v_pk_mul_f32 v[48:49], v[48:49], v[48:49]
	v_add_f32_e32 v34, v35, v34
	v_add_f32_e32 v35, v56, v57
	v_add_f32_e32 v36, v54, v55
	v_add_f32_e32 v35, v36, v35
	v_add_f32_e32 v36, v48, v49
	v_add_f32_e32 v37, v46, v47
	v_add_f32_e32 v36, v37, v36
	v_add_f32_e32 v35, v36, v35
	v_add_f32_e32 v34, v35, v34
	v_mov_b32_e32 v35, v34
	s_nop 1
	v_permlane16_swap_b32_e32 v34, v35
	global_store_dwordx4 v[52:53], v[42:45], off offset:256
	s_waitcnt lgkmcnt(0)
	v_add_f32_e32 v34, v34, v35
	v_mov_b32_e32 v35, v34
	s_nop 1
	v_permlane32_swap_b32_e32 v34, v35
	s_and_saveexec_b64 s[24:25], s[6:7]
	s_cbranch_execz .LBB0_878
	v_lshlrev_b64 v[36:37], 6, v[50:51]
	v_lshl_add_u64 v[36:37], s[14:15], 0, v[36:37]
	v_lshl_add_u64 v[36:37], s[22:23], 2, v[36:37]
	s_lshl_b32 s72, s40, 2
	v_lshl_add_u64 v[36:37], v[36:37], 0, s[72:73]
	s_waitcnt lgkmcnt(0)
	v_add_f32_e32 v34, v34, v35
	global_store_dword v[36:37], v34, off

; #define GAS __attribute__((address_space(1)))
; __device__ __forceinline__ unsigned cvt_pk_bf16(float lo, float hi) { f32x2 v = {lo, hi}; bf16x2_t b = __builtin_convertvector(v, bf16x2_t); return __builtin_bit_cast(unsigned, b); }
; __device__ __forceinline__ float bf_lo(unsigned u) { return __uint_as_float(u << 16); }
; __device__ __forceinline__ float bf_hi(unsigned u) { return __uint_as_float(u & 0xffff0000u); }
;     __device__ __forceinline__ void operator()(const f32x4 (&acc)[2][2][4][2], const Unit& u, int wr, int wc, int fr, int fq) const {
;     ...
;                 for (int bj = 0; bj < 2; ++bj) { const u32x4 xo = *(const GAS u32x4*)(xb + off + bj * HALF);
;                     f32x4 v0 = acc[ai][bj][m][0], v1 = acc[ai][bj][m][1];
;                     v0[0] += bf_lo(xo.x); v0[1] += bf_hi(xo.x); v0[2] += bf_lo(xo.y); v0[3] += bf_hi(xo.y); v1[0] += bf_lo(xo.z); v1[1] += bf_hi(xo.z); v1[2] += bf_lo(xo.w); v1[3] += bf_hi(xo.w);
;                     if (out) { *(GAS f32x4*)(out + off + bj * HALF) = v0; *(GAS f32x4*)(out + off + bj * HALF + 4) = v1; }
;                     u32x4 w; w.x = cvt_pk_bf16(v0[0], v0[1]); w.y = cvt_pk_bf16(v0[2], v0[3]); w.z = cvt_pk_bf16(v1[0], v1[1]); w.w = cvt_pk_bf16(v1[2], v1[3]);
;                     *(GAS u32x4*)(xb + off + bj * HALF) = w;
;                     q += ((v0[0] * v0[0] + v0[1] * v0[1]) + (v0[2] * v0[2] + v0[3] * v0[3])) + ((v1[0] * v1[0] + v1[1] * v1[1]) + (v1[2] * v1[2] + v1[3] * v1[3])); }
;                 q += __shfl_xor(q, 16); q += __shfl_xor(q, 32);
;                 if (fq == 0) rowss[(size_t)row * 16 + u.pn * 4 + wc] = q; }
.LBB0_882:
	v_pk_mul_f32 v[40:41], v[28:29], v[28:29]
	v_cvt_pk_bf16_f32 v28, v18, v19
	v_cvt_pk_bf16_f32 v29, v20, v21
	v_pk_mul_f32 v[18:19], v[18:19], v[18:19]
	v_pk_mul_f32 v[20:21], v[20:21], v[20:21]
	v_pk_mul_f32 v[38:39], v[26:27], v[26:27]
	v_cvt_pk_bf16_f32 v26, v22, v23
	v_cvt_pk_bf16_f32 v27, v24, v25
	v_pk_mul_f32 v[22:23], v[22:23], v[22:23]
	v_pk_mul_f32 v[24:25], v[24:25], v[24:25]
	v_add_f32_e32 v20, v20, v21
	v_add_f32_e32 v18, v18, v19
	v_add_f32_e32 v18, v18, v20
	v_add_f32_e32 v19, v24, v25
	v_add_f32_e32 v20, v22, v23
	v_add_f32_e32 v19, v20, v19
	v_pk_mul_f32 v[30:31], v[30:31], v[30:31]
	v_pk_mul_f32 v[32:33], v[32:33], v[32:33]
	v_add_f32_e32 v18, v19, v18
	v_add_f32_e32 v19, v40, v41
	v_add_f32_e32 v20, v38, v39
	v_add_f32_e32 v19, v20, v19
	v_add_f32_e32 v20, v32, v33
	v_add_f32_e32 v21, v30, v31
	v_add_f32_e32 v20, v21, v20
	v_add_f32_e32 v19, v20, v19
	v_add_f32_e32 v18, v19, v18
	v_mov_b32_e32 v19, v18
	s_nop 1
	v_permlane16_swap_b32_e32 v18, v19
	global_store_dwordx4 v[36:37], v[26:29], off offset:256
	s_waitcnt lgkmcnt(0)
	v_add_f32_e32 v18, v18, v19
	v_mov_b32_e32 v19, v18
	s_nop 1
	v_permlane32_swap_b32_e32 v18, v19
	s_and_saveexec_b64 s[24:25], s[6:7]
	s_cbranch_execz .LBB0_884
	v_lshlrev_b64 v[20:21], 6, v[34:35]
	v_lshl_add_u64 v[20:21], s[14:15], 0, v[20:21]
	v_lshl_add_u64 v[20:21], s[22:23], 2, v[20:21]
	s_lshl_b32 s72, s40, 2
	v_lshl_add_u64 v[20:21], v[20:21], 0, s[72:73]
	s_waitcnt lgkmcnt(0)
	v_add_f32_e32 v18, v18, v19
	global_store_dword v[20:21], v18, off

; #define GAS __attribute__((address_space(1)))
; __device__ __forceinline__ unsigned cvt_pk_bf16(float lo, float hi) { f32x2 v = {lo, hi}; bf16x2_t b = __builtin_convertvector(v, bf16x2_t); return __builtin_bit_cast(unsigned, b); }
; __device__ __forceinline__ float bf_lo(unsigned u) { return __uint_as_float(u << 16); }
; __device__ __forceinline__ float bf_hi(unsigned u) { return __uint_as_float(u & 0xffff0000u); }
;     __device__ __forceinline__ void operator()(const f32x4 (&acc)[2][2][4][2], const Unit& u, int wr, int wc, int fr, int fq) const {
;     ...
;                 for (int bj = 0; bj < 2; ++bj) { const u32x4 xo = *(const GAS u32x4*)(xb + off + bj * HALF);
;                     f32x4 v0 = acc[ai][bj][m][0], v1 = acc[ai][bj][m][1];
;                     v0[0] += bf_lo(xo.x); v0[1] += bf_hi(xo.x); v0[2] += bf_lo(xo.y); v0[3] += bf_hi(xo.y); v1[0] += bf_lo(xo.z); v1[1] += bf_hi(xo.z); v1[2] += bf_lo(xo.w); v1[3] += bf_hi(xo.w);
;                     if (out) { *(GAS f32x4*)(out + off + bj * HALF) = v0; *(GAS f32x4*)(out + off + bj * HALF + 4) = v1; }
;                     u32x4 w; w.x = cvt_pk_bf16(v0[0], v0[1]); w.y = cvt_pk_bf16(v0[2], v0[3]); w.z = cvt_pk_bf16(v1[0], v1[1]); w.w = cvt_pk_bf16(v1[2], v1[3]);
;                     *(GAS u32x4*)(xb + off + bj * HALF) = w;
;                     q += ((v0[0] * v0[0] + v0[1] * v0[1]) + (v0[2] * v0[2] + v0[3] * v0[3])) + ((v1[0] * v1[0] + v1[1] * v1[1]) + (v1[2] * v1[2] + v1[3] * v1[3])); }
;                 q += __shfl_xor(q, 16); q += __shfl_xor(q, 32);
;                 if (fq == 0) rowss[(size_t)row * 16 + u.pn * 4 + wc] = q; }
.LBB0_888:
	v_pk_mul_f32 v[24:25], v[12:13], v[12:13]
	v_cvt_pk_bf16_f32 v12, v2, v3
	v_cvt_pk_bf16_f32 v13, v4, v5
	v_pk_mul_f32 v[2:3], v[2:3], v[2:3]
	v_pk_mul_f32 v[4:5], v[4:5], v[4:5]
	v_pk_mul_f32 v[22:23], v[10:11], v[10:11]
	v_cvt_pk_bf16_f32 v10, v6, v7
	v_cvt_pk_bf16_f32 v11, v8, v9
	v_pk_mul_f32 v[6:7], v[6:7], v[6:7]
	v_pk_mul_f32 v[8:9], v[8:9], v[8:9]
	v_add_f32_e32 v4, v4, v5
	v_add_f32_e32 v2, v2, v3
	v_add_f32_e32 v2, v2, v4
	v_add_f32_e32 v3, v8, v9
	v_add_f32_e32 v4, v6, v7
	v_add_f32_e32 v3, v4, v3
	v_pk_mul_f32 v[14:15], v[14:15], v[14:15]
	v_pk_mul_f32 v[16:17], v[16:17], v[16:17]
	v_add_f32_e32 v2, v3, v2
	v_add_f32_e32 v3, v24, v25
	v_add_f32_e32 v4, v22, v23
	v_add_f32_e32 v3, v4, v3
	v_add_f32_e32 v4, v16, v17
	v_add_f32_e32 v5, v14, v15
	v_add_f32_e32 v4, v5, v4
	v_add_f32_e32 v3, v4, v3
	v_add_f32_e32 v2, v3, v2
	v_mov_b32_e32 v3, v2
	s_nop 1
	v_permlane16_swap_b32_e32 v2, v3
	global_store_dwordx4 v[20:21], v[10:13], off offset:256
	s_waitcnt lgkmcnt(0)
	v_add_f32_e32 v2, v2, v3
	v_mov_b32_e32 v3, v2
	s_nop 1
	v_permlane32_swap_b32_e32 v2, v3
	s_and_saveexec_b64 s[10:11], s[6:7]
	s_cbranch_execz .LBB0_890
	v_lshlrev_b64 v[4:5], 6, v[18:19]
	v_lshl_add_u64 v[4:5], s[14:15], 0, v[4:5]
	v_lshl_add_u64 v[4:5], s[22:23], 2, v[4:5]
	s_lshl_b32 s72, s40, 2
	v_lshl_add_u64 v[4:5], v[4:5], 0, s[72:73]
	s_waitcnt lgkmcnt(0)
	v_add_f32_e32 v2, v2, v3
	global_store_dword v[4:5], v2, off
